# k5 variant: s_setprio flips removed from the merged GEMM K-loops
# baseline (speedup 1.0000x reference)
.LBB0_670:
	ds_read_b128 v[154:157], v150
	ds_read_b128 v[158:161], v150 offset:1024
	ds_read_b128 v[162:165], v150 offset:2048
	ds_read_b128 v[166:169], v150 offset:3072
	ds_read_b128 v[202:205], v152
	ds_read_b128 v[206:209], v152 offset:1024
	ds_read_b128 v[210:213], v152 offset:2048
	ds_read_b128 v[214:217], v152 offset:3072
	s_add_u32 s28, s34, 0xfff00080
	s_addc_u32 s29, s35, -1
	s_cmp_eq_u32 s94, 60
	s_cselect_b32 s39, s23, s29
	s_cselect_b32 s38, s22, s28
	s_cselect_b32 s37, s21, s93
	s_cselect_b32 s36, s20, s19
	v_lshl_add_u64 v[146:147], s[34:35], 0, v[142:143]
	s_add_i32 m0, s27, 0xc000
	ds_read_b128 v[170:173], v151
	ds_read_b128 v[174:177], v151 offset:1024
	ds_read_b128 v[178:181], v151 offset:2048
	ds_read_b128 v[182:185], v151 offset:3072
	ds_read_b128 v[186:189], v151 offset:4096
	ds_read_b128 v[190:193], v151 offset:5120
	ds_read_b128 v[194:197], v151 offset:6144
	ds_read_b128 v[198:201], v151 offset:7168
	global_load_lds_dwordx4 v[146:147], off
	v_lshl_add_u64 v[146:147], s[34:35], 0, v[140:141]
	s_add_i32 m0, s27, 0xe000
	s_nop 0
	global_load_lds_dwordx4 v[146:147], off
	s_waitcnt vmcnt(8)
	s_waitcnt lgkmcnt(0)
	s_barrier
	v_mfma_f32_16x16x32_bf16 v[126:129], v[154:157], v[170:173], v[126:129]
	v_mfma_f32_16x16x32_bf16 v[122:125], v[162:165], v[170:173], v[122:125]
	v_mfma_f32_16x16x32_bf16 v[118:121], v[154:157], v[178:181], v[118:121]
	v_mfma_f32_16x16x32_bf16 v[110:113], v[162:165], v[178:181], v[110:113]
	v_mfma_f32_16x16x32_bf16 v[102:105], v[154:157], v[186:189], v[102:105]
	v_mfma_f32_16x16x32_bf16 v[94:97], v[162:165], v[186:189], v[94:97]
	v_mfma_f32_16x16x32_bf16 v[86:89], v[154:157], v[194:197], v[86:89]
	v_mfma_f32_16x16x32_bf16 v[78:81], v[162:165], v[194:197], v[78:81]
	v_mfma_f32_16x16x32_bf16 v[126:129], v[158:161], v[174:177], v[126:129]
	v_mfma_f32_16x16x32_bf16 v[122:125], v[166:169], v[174:177], v[122:125]
	v_mfma_f32_16x16x32_bf16 v[118:121], v[158:161], v[182:185], v[118:121]
	v_mfma_f32_16x16x32_bf16 v[110:113], v[166:169], v[182:185], v[110:113]
	v_mfma_f32_16x16x32_bf16 v[102:105], v[158:161], v[190:193], v[102:105]
	v_mfma_f32_16x16x32_bf16 v[94:97], v[166:169], v[190:193], v[94:97]
	v_mfma_f32_16x16x32_bf16 v[86:89], v[158:161], v[198:201], v[86:89]
	v_mfma_f32_16x16x32_bf16 v[78:81], v[166:169], v[198:201], v[78:81]
	v_mfma_f32_16x16x32_bf16 v[114:117], v[202:205], v[170:173], v[114:117]
	v_mfma_f32_16x16x32_bf16 v[106:109], v[210:213], v[170:173], v[106:109]
	v_mfma_f32_16x16x32_bf16 v[98:101], v[202:205], v[178:181], v[98:101]
	v_mfma_f32_16x16x32_bf16 v[90:93], v[210:213], v[178:181], v[90:93]
	v_mfma_f32_16x16x32_bf16 v[82:85], v[202:205], v[186:189], v[82:85]
	v_mfma_f32_16x16x32_bf16 v[74:77], v[210:213], v[186:189], v[74:77]
	v_mfma_f32_16x16x32_bf16 v[70:73], v[202:205], v[194:197], v[70:73]
	v_mfma_f32_16x16x32_bf16 v[66:69], v[210:213], v[194:197], v[66:69]
	v_mfma_f32_16x16x32_bf16 v[114:117], v[206:209], v[174:177], v[114:117]
	v_mfma_f32_16x16x32_bf16 v[106:109], v[214:217], v[174:177], v[106:109]
	v_mfma_f32_16x16x32_bf16 v[98:101], v[206:209], v[182:185], v[98:101]
	v_mfma_f32_16x16x32_bf16 v[90:93], v[214:217], v[182:185], v[90:93]
	v_mfma_f32_16x16x32_bf16 v[82:85], v[206:209], v[190:193], v[82:85]
	v_mfma_f32_16x16x32_bf16 v[74:77], v[214:217], v[190:193], v[74:77]
	v_mfma_f32_16x16x32_bf16 v[70:73], v[206:209], v[198:201], v[70:73]
	v_mfma_f32_16x16x32_bf16 v[66:69], v[214:217], v[198:201], v[66:69]
	s_barrier
	ds_read_b128 v[170:173], v151 offset:16384
	ds_read_b128 v[174:177], v151 offset:17408
	ds_read_b128 v[178:181], v151 offset:18432
	ds_read_b128 v[182:185], v151 offset:19456
	ds_read_b128 v[186:189], v151 offset:20480
	ds_read_b128 v[190:193], v151 offset:21504
	ds_read_b128 v[194:197], v151 offset:22528
	ds_read_b128 v[198:201], v151 offset:23552
	s_add_i32 s28, s85, s74
	v_lshl_add_u64 v[146:147], s[36:37], 0, v[134:135]
	s_mov_b32 m0, s28
	s_nop 0
	global_load_lds_dwordx4 v[146:147], off
	v_lshl_add_u64 v[218:219], s[36:37], 0, v[130:131]
	s_add_i32 m0, s28, 0x2000
	s_nop 0
	global_load_lds_dwordx4 v[218:219], off
	s_mov_b32 m0, s27
	v_lshl_add_u64 v[220:221], s[38:39], 0, v[136:137]
	global_load_lds_dwordx4 v[220:221], off
	v_lshl_add_u64 v[222:223], s[38:39], 0, v[132:133]
	s_mov_b32 m0, s76
	s_nop 0
	global_load_lds_dwordx4 v[222:223], off
	s_add_u32 s28, s36, 0x100000
	s_addc_u32 s29, s37, 0
	s_add_i32 s95, s86, s74
	v_lshl_add_u64 v[226:227], s[28:29], 0, v[134:135]
	s_mov_b32 m0, s95
	s_nop 0
	global_load_lds_dwordx4 v[226:227], off
	v_lshl_add_u64 v[226:227], s[28:29], 0, v[130:131]
	s_add_i32 m0, s95, 0x2000
	s_nop 0
	global_load_lds_dwordx4 v[226:227], off
	s_waitcnt vmcnt(8)
	s_waitcnt lgkmcnt(0)
	s_barrier
	v_mfma_f32_16x16x32_bf16 v[62:65], v[154:157], v[170:173], v[62:65]
	v_mfma_f32_16x16x32_bf16 v[58:61], v[162:165], v[170:173], v[58:61]
	v_mfma_f32_16x16x32_bf16 v[54:57], v[154:157], v[178:181], v[54:57]
	v_mfma_f32_16x16x32_bf16 v[46:49], v[162:165], v[178:181], v[46:49]
	v_mfma_f32_16x16x32_bf16 v[38:41], v[154:157], v[186:189], v[38:41]
	v_mfma_f32_16x16x32_bf16 v[30:33], v[162:165], v[186:189], v[30:33]
	v_mfma_f32_16x16x32_bf16 v[22:25], v[154:157], v[194:197], v[22:25]
	v_mfma_f32_16x16x32_bf16 v[14:17], v[162:165], v[194:197], v[14:17]
	v_mfma_f32_16x16x32_bf16 v[62:65], v[158:161], v[174:177], v[62:65]
	v_mfma_f32_16x16x32_bf16 v[58:61], v[166:169], v[174:177], v[58:61]
	v_mfma_f32_16x16x32_bf16 v[54:57], v[158:161], v[182:185], v[54:57]
	v_mfma_f32_16x16x32_bf16 v[46:49], v[166:169], v[182:185], v[46:49]
	v_mfma_f32_16x16x32_bf16 v[38:41], v[158:161], v[190:193], v[38:41]
	v_mfma_f32_16x16x32_bf16 v[30:33], v[166:169], v[190:193], v[30:33]
	v_mfma_f32_16x16x32_bf16 v[22:25], v[158:161], v[198:201], v[22:25]
	v_mfma_f32_16x16x32_bf16 v[14:17], v[166:169], v[198:201], v[14:17]
	v_mfma_f32_16x16x32_bf16 v[50:53], v[202:205], v[170:173], v[50:53]
	v_mfma_f32_16x16x32_bf16 v[42:45], v[210:213], v[170:173], v[42:45]
	v_mfma_f32_16x16x32_bf16 v[34:37], v[202:205], v[178:181], v[34:37]
	v_mfma_f32_16x16x32_bf16 v[26:29], v[210:213], v[178:181], v[26:29]
	v_mfma_f32_16x16x32_bf16 v[18:21], v[202:205], v[186:189], v[18:21]
	v_mfma_f32_16x16x32_bf16 v[10:13], v[210:213], v[186:189], v[10:13]
	v_mfma_f32_16x16x32_bf16 v[6:9], v[202:205], v[194:197], v[6:9]
	v_mfma_f32_16x16x32_bf16 v[2:5], v[210:213], v[194:197], v[2:5]
	v_mfma_f32_16x16x32_bf16 v[50:53], v[206:209], v[174:177], v[50:53]
	v_mfma_f32_16x16x32_bf16 v[42:45], v[214:217], v[174:177], v[42:45]
	v_mfma_f32_16x16x32_bf16 v[34:37], v[206:209], v[182:185], v[34:37]
	v_mfma_f32_16x16x32_bf16 v[26:29], v[214:217], v[182:185], v[26:29]
	v_mfma_f32_16x16x32_bf16 v[18:21], v[206:209], v[190:193], v[18:21]
	v_mfma_f32_16x16x32_bf16 v[10:13], v[214:217], v[190:193], v[10:13]
	v_mfma_f32_16x16x32_bf16 v[6:9], v[206:209], v[198:201], v[6:9]
	v_mfma_f32_16x16x32_bf16 v[2:5], v[214:217], v[198:201], v[2:5]
	s_add_i32 s95, 0, 0x18000
	v_add_u32_e32 v153, s95, v148
	s_barrier
	ds_read_b128 v[154:157], v153
	ds_read_b128 v[158:161], v153 offset:1024
	ds_read_b128 v[162:165], v153 offset:2048
	ds_read_b128 v[166:169], v153 offset:3072
	ds_read_b128 v[202:205], v153 offset:16384
	ds_read_b128 v[206:209], v153 offset:17408
	ds_read_b128 v[210:213], v153 offset:18432
	ds_read_b128 v[214:217], v153 offset:19456
	s_add_u32 s28, s38, 0x100000
	s_addc_u32 s29, s39, 0
	s_mov_b32 m0, s77
	v_lshl_add_u64 v[226:227], s[28:29], 0, v[136:137]
	ds_read_b128 v[170:173], v151 offset:32768
	ds_read_b128 v[174:177], v151 offset:33792
	ds_read_b128 v[178:181], v151 offset:34816
	ds_read_b128 v[182:185], v151 offset:35840
	ds_read_b128 v[186:189], v151 offset:36864
	ds_read_b128 v[190:193], v151 offset:37888
	ds_read_b128 v[194:197], v151 offset:38912
	ds_read_b128 v[198:201], v151 offset:39936
	global_load_lds_dwordx4 v[226:227], off
	v_lshl_add_u64 v[226:227], s[28:29], 0, v[132:133]
	s_mov_b32 m0, s78
	s_nop 0
	global_load_lds_dwordx4 v[226:227], off
	s_waitcnt vmcnt(8)
	s_waitcnt lgkmcnt(0)
	s_barrier
	v_mfma_f32_16x16x32_bf16 v[126:129], v[154:157], v[170:173], v[126:129]
	v_mfma_f32_16x16x32_bf16 v[122:125], v[162:165], v[170:173], v[122:125]
	v_mfma_f32_16x16x32_bf16 v[118:121], v[154:157], v[178:181], v[118:121]
	v_mfma_f32_16x16x32_bf16 v[110:113], v[162:165], v[178:181], v[110:113]
	v_mfma_f32_16x16x32_bf16 v[102:105], v[154:157], v[186:189], v[102:105]
	v_mfma_f32_16x16x32_bf16 v[94:97], v[162:165], v[186:189], v[94:97]
	v_mfma_f32_16x16x32_bf16 v[86:89], v[154:157], v[194:197], v[86:89]
	v_mfma_f32_16x16x32_bf16 v[78:81], v[162:165], v[194:197], v[78:81]
	v_mfma_f32_16x16x32_bf16 v[126:129], v[158:161], v[174:177], v[126:129]
	v_mfma_f32_16x16x32_bf16 v[122:125], v[166:169], v[174:177], v[122:125]
	v_mfma_f32_16x16x32_bf16 v[118:121], v[158:161], v[182:185], v[118:121]
	v_mfma_f32_16x16x32_bf16 v[110:113], v[166:169], v[182:185], v[110:113]
	v_mfma_f32_16x16x32_bf16 v[102:105], v[158:161], v[190:193], v[102:105]
	v_mfma_f32_16x16x32_bf16 v[94:97], v[166:169], v[190:193], v[94:97]
	v_mfma_f32_16x16x32_bf16 v[86:89], v[158:161], v[198:201], v[86:89]
	v_mfma_f32_16x16x32_bf16 v[78:81], v[166:169], v[198:201], v[78:81]
	v_mfma_f32_16x16x32_bf16 v[114:117], v[202:205], v[170:173], v[114:117]
	v_mfma_f32_16x16x32_bf16 v[106:109], v[210:213], v[170:173], v[106:109]
	v_mfma_f32_16x16x32_bf16 v[98:101], v[202:205], v[178:181], v[98:101]
	v_mfma_f32_16x16x32_bf16 v[90:93], v[210:213], v[178:181], v[90:93]
	v_mfma_f32_16x16x32_bf16 v[82:85], v[202:205], v[186:189], v[82:85]
	v_mfma_f32_16x16x32_bf16 v[74:77], v[210:213], v[186:189], v[74:77]
	v_mfma_f32_16x16x32_bf16 v[70:73], v[202:205], v[194:197], v[70:73]
	v_mfma_f32_16x16x32_bf16 v[66:69], v[210:213], v[194:197], v[66:69]
	v_mfma_f32_16x16x32_bf16 v[114:117], v[206:209], v[174:177], v[114:117]
	v_mfma_f32_16x16x32_bf16 v[106:109], v[214:217], v[174:177], v[106:109]
	v_mfma_f32_16x16x32_bf16 v[98:101], v[206:209], v[182:185], v[98:101]
	v_mfma_f32_16x16x32_bf16 v[90:93], v[214:217], v[182:185], v[90:93]
	v_mfma_f32_16x16x32_bf16 v[82:85], v[206:209], v[190:193], v[82:85]
	v_mfma_f32_16x16x32_bf16 v[74:77], v[214:217], v[190:193], v[74:77]
	v_mfma_f32_16x16x32_bf16 v[70:73], v[206:209], v[198:201], v[70:73]
	v_mfma_f32_16x16x32_bf16 v[66:69], v[214:217], v[198:201], v[66:69]
	s_barrier
	ds_read_b128 v[170:173], v151 offset:49152
	ds_read_b128 v[174:177], v151 offset:50176
	ds_read_b128 v[178:181], v151 offset:51200
	ds_read_b128 v[182:185], v151 offset:52224
	ds_read_b128 v[186:189], v151 offset:53248
	ds_read_b128 v[190:193], v151 offset:54272
	ds_read_b128 v[194:197], v151 offset:55296
	ds_read_b128 v[198:201], v151 offset:56320
	s_add_i32 s38, 0, 0x1c000
	s_add_i32 s28, s95, s74
	v_lshl_add_u64 v[146:147], v[146:147], 0, s[0:1]
	s_mov_b32 m0, s28
	s_nop 0
	global_load_lds_dwordx4 v[146:147], off
	v_lshl_add_u64 v[146:147], v[218:219], 0, s[0:1]
	s_add_i32 m0, s28, 0x2000
	s_nop 0
	global_load_lds_dwordx4 v[146:147], off
	s_mov_b32 m0, s80
	v_lshl_add_u64 v[146:147], v[220:221], 0, s[0:1]
	global_load_lds_dwordx4 v[146:147], off
	v_lshl_add_u64 v[146:147], v[222:223], 0, s[0:1]
	s_mov_b32 m0, s81
	s_nop 0
	global_load_lds_dwordx4 v[146:147], off
	s_add_u32 s28, s36, 0x100080
	s_addc_u32 s29, s37, 0
	s_add_i32 s36, s38, s74
	v_lshl_add_u64 v[146:147], s[28:29], 0, v[134:135]
	s_mov_b32 m0, s36
	s_nop 0
	global_load_lds_dwordx4 v[146:147], off
	v_lshl_add_u64 v[146:147], s[28:29], 0, v[130:131]
	s_add_i32 m0, s36, 0x2000
	s_nop 0
	global_load_lds_dwordx4 v[146:147], off
	s_waitcnt vmcnt(8)
	s_waitcnt lgkmcnt(0)
	s_barrier
	v_mfma_f32_16x16x32_bf16 v[62:65], v[154:157], v[170:173], v[62:65]
	v_mfma_f32_16x16x32_bf16 v[58:61], v[162:165], v[170:173], v[58:61]
	v_mfma_f32_16x16x32_bf16 v[54:57], v[154:157], v[178:181], v[54:57]
	v_mfma_f32_16x16x32_bf16 v[46:49], v[162:165], v[178:181], v[46:49]
	v_mfma_f32_16x16x32_bf16 v[38:41], v[154:157], v[186:189], v[38:41]
	v_mfma_f32_16x16x32_bf16 v[30:33], v[162:165], v[186:189], v[30:33]
	v_mfma_f32_16x16x32_bf16 v[22:25], v[154:157], v[194:197], v[22:25]
	v_mfma_f32_16x16x32_bf16 v[14:17], v[162:165], v[194:197], v[14:17]
	v_mfma_f32_16x16x32_bf16 v[62:65], v[158:161], v[174:177], v[62:65]
	v_mfma_f32_16x16x32_bf16 v[58:61], v[166:169], v[174:177], v[58:61]
	v_mfma_f32_16x16x32_bf16 v[54:57], v[158:161], v[182:185], v[54:57]
	v_mfma_f32_16x16x32_bf16 v[46:49], v[166:169], v[182:185], v[46:49]
	v_mfma_f32_16x16x32_bf16 v[38:41], v[158:161], v[190:193], v[38:41]
	v_mfma_f32_16x16x32_bf16 v[30:33], v[166:169], v[190:193], v[30:33]
	v_mfma_f32_16x16x32_bf16 v[22:25], v[158:161], v[198:201], v[22:25]
	v_mfma_f32_16x16x32_bf16 v[14:17], v[166:169], v[198:201], v[14:17]
	v_mfma_f32_16x16x32_bf16 v[50:53], v[202:205], v[170:173], v[50:53]
	v_mfma_f32_16x16x32_bf16 v[42:45], v[210:213], v[170:173], v[42:45]
	v_mfma_f32_16x16x32_bf16 v[34:37], v[202:205], v[178:181], v[34:37]
	v_mfma_f32_16x16x32_bf16 v[26:29], v[210:213], v[178:181], v[26:29]
	v_mfma_f32_16x16x32_bf16 v[18:21], v[202:205], v[186:189], v[18:21]
	v_mfma_f32_16x16x32_bf16 v[10:13], v[210:213], v[186:189], v[10:13]
	v_mfma_f32_16x16x32_bf16 v[6:9], v[202:205], v[194:197], v[6:9]
	v_mfma_f32_16x16x32_bf16 v[2:5], v[210:213], v[194:197], v[2:5]
	v_mfma_f32_16x16x32_bf16 v[50:53], v[206:209], v[174:177], v[50:53]
	v_mfma_f32_16x16x32_bf16 v[42:45], v[214:217], v[174:177], v[42:45]
	v_mfma_f32_16x16x32_bf16 v[34:37], v[206:209], v[182:185], v[34:37]
	v_mfma_f32_16x16x32_bf16 v[26:29], v[214:217], v[182:185], v[26:29]
	v_mfma_f32_16x16x32_bf16 v[18:21], v[206:209], v[190:193], v[18:21]
	v_mfma_f32_16x16x32_bf16 v[10:13], v[214:217], v[190:193], v[10:13]
	v_mfma_f32_16x16x32_bf16 v[6:9], v[206:209], v[198:201], v[6:9]
	v_mfma_f32_16x16x32_bf16 v[2:5], v[214:217], v[198:201], v[2:5]
	s_add_i32 s94, s94, 2
	s_add_u32 s19, s19, 0x100
	s_addc_u32 s93, s93, 0
	s_add_u32 s34, s34, 0x100
	s_addc_u32 s35, s35, 0
	s_cmp_gt_u32 s94, 61
	s_barrier
	s_cbranch_scc0 .LBB0_670
	s_cmp_lt_i32 s92, 2
	s_cbranch_scc1 .LBB0_675
	s_cmp_eq_u32 s92, 2
	s_mov_b64 s[34:35], -1
	s_cbranch_scc0 .LBB0_674
	v_lshl_add_u32 v146, s26, 8, v1
	v_or_b32_e32 v156, 16, v146
	v_ashrrev_i32_e32 v147, 31, v146
	v_ashrrev_i32_e32 v157, 31, v156
	v_lshlrev_b64 v[154:155], 10, v[146:147]
	v_lshlrev_b64 v[156:157], 10, v[156:157]
	v_lshl_add_u64 v[154:155], v[138:139], 0, v[154:155]
	v_lshl_add_u64 v[156:157], v[138:139], 0, v[156:157]
	global_store_dwordx4 v[154:155], v[126:129], off
	global_store_dwordx4 v[154:155], v[122:125], off offset:16
	global_store_dwordx4 v[154:155], v[114:117], off offset:512
	global_store_dwordx4 v[154:155], v[106:109], off offset:528
	global_store_dwordx4 v[156:157], v[118:121], off
	global_store_dwordx4 v[156:157], v[110:113], off offset:16
	global_store_dwordx4 v[156:157], v[98:101], off offset:512
	global_store_dwordx4 v[156:157], v[90:93], off offset:528
	v_or_b32_e32 v156, 32, v146
	v_ashrrev_i32_e32 v157, 31, v156
	v_lshlrev_b64 v[156:157], 10, v[156:157]
	v_or_b32_e32 v146, 48, v146
	v_lshl_add_u64 v[156:157], v[138:139], 0, v[156:157]
	v_ashrrev_i32_e32 v147, 31, v146
	global_store_dwordx4 v[156:157], v[102:105], off
	global_store_dwordx4 v[156:157], v[94:97], off offset:16
	global_store_dwordx4 v[156:157], v[82:85], off offset:512
	global_store_dwordx4 v[156:157], v[74:77], off offset:528
	v_lshlrev_b64 v[146:147], 10, v[146:147]
	v_add_co_u32_e32 v156, vcc, s87, v154
	v_lshl_add_u64 v[146:147], v[138:139], 0, v[146:147]
	s_mov_b64 s[28:29], 0x20000
	v_addc_co_u32_e32 v157, vcc, 0, v155, vcc
	global_store_dwordx4 v[146:147], v[86:89], off
	global_store_dwordx4 v[146:147], v[78:81], off offset:16
	global_store_dwordx4 v[146:147], v[70:73], off offset:512
	global_store_dwordx4 v[146:147], v[66:69], off offset:528
	v_lshl_add_u64 v[146:147], v[154:155], 0, s[28:29]
	global_store_dwordx4 v[156:157], v[62:65], off
	global_store_dwordx4 v[146:147], v[58:61], off offset:16
	global_store_dwordx4 v[146:147], v[50:53], off offset:512
	global_store_dwordx4 v[146:147], v[42:45], off offset:528
	v_add_co_u32_e32 v156, vcc, s88, v154
	v_lshl_add_u64 v[146:147], v[154:155], 0, s[6:7]
	s_nop 0
	v_addc_co_u32_e32 v157, vcc, 0, v155, vcc
	global_store_dwordx4 v[156:157], v[54:57], off
	global_store_dwordx4 v[146:147], v[46:49], off offset:16
	global_store_dwordx4 v[146:147], v[34:37], off offset:512
	global_store_dwordx4 v[146:147], v[26:29], off offset:528
	v_add_co_u32_e32 v156, vcc, s89, v154
	v_lshl_add_u64 v[146:147], v[154:155], 0, s[12:13]
	s_nop 0
	v_addc_co_u32_e32 v157, vcc, 0, v155, vcc
	global_store_dwordx4 v[156:157], v[38:41], off
	global_store_dwordx4 v[146:147], v[30:33], off offset:16
	global_store_dwordx4 v[146:147], v[18:21], off offset:512
	global_store_dwordx4 v[146:147], v[10:13], off offset:528
	v_lshl_add_u64 v[146:147], v[154:155], 0, s[14:15]
	v_add_co_u32_e32 v154, vcc, 0x2c000, v154
	s_mov_b64 s[34:35], 0
	s_nop 0
	v_addc_co_u32_e32 v155, vcc, 0, v155, vcc
	global_store_dwordx4 v[154:155], v[22:25], off
	global_store_dwordx4 v[146:147], v[14:17], off offset:16
	global_store_dwordx4 v[146:147], v[6:9], off offset:512
	global_store_dwordx4 v[146:147], v[2:5], off offset:528

.LBB0_2485:
	ds_read_b128 v[152:155], v148
	ds_read_b128 v[156:159], v148 offset:1024
	ds_read_b128 v[160:163], v148 offset:2048
	ds_read_b128 v[164:167], v148 offset:3072
	ds_read_b128 v[200:203], v150
	ds_read_b128 v[204:207], v150 offset:1024
	ds_read_b128 v[208:211], v150 offset:2048
	ds_read_b128 v[212:215], v150 offset:3072
	s_add_u32 s28, s50, 0xfff00080
	s_addc_u32 s29, s51, -1
	s_cmp_eq_u32 s81, 60
	s_cselect_b32 s55, s45, s29
	s_cselect_b32 s54, s44, s28
	s_cselect_b32 s53, s47, s41
	s_cselect_b32 s52, s46, s39
	v_lshl_add_u64 v[144:145], s[50:51], 0, v[140:141]
	s_add_i32 m0, s49, 0xc000
	ds_read_b128 v[168:171], v149
	ds_read_b128 v[172:175], v149 offset:1024
	ds_read_b128 v[176:179], v149 offset:2048
	ds_read_b128 v[180:183], v149 offset:3072
	ds_read_b128 v[184:187], v149 offset:4096
	ds_read_b128 v[188:191], v149 offset:5120
	ds_read_b128 v[192:195], v149 offset:6144
	ds_read_b128 v[196:199], v149 offset:7168
	global_load_lds_dwordx4 v[144:145], off
	v_lshl_add_u64 v[144:145], s[50:51], 0, v[138:139]
	s_add_i32 m0, s49, 0xe000
	s_nop 0
	global_load_lds_dwordx4 v[144:145], off
	s_waitcnt vmcnt(8)
	s_waitcnt lgkmcnt(0)
	s_barrier
	v_mfma_f32_16x16x32_bf16 v[126:129], v[152:155], v[168:171], v[126:129]
	v_mfma_f32_16x16x32_bf16 v[122:125], v[160:163], v[168:171], v[122:125]
	v_mfma_f32_16x16x32_bf16 v[114:117], v[152:155], v[176:179], v[114:117]
	v_mfma_f32_16x16x32_bf16 v[106:109], v[160:163], v[176:179], v[106:109]
	v_mfma_f32_16x16x32_bf16 v[98:101], v[152:155], v[184:187], v[98:101]
	v_mfma_f32_16x16x32_bf16 v[90:93], v[160:163], v[184:187], v[90:93]
	v_mfma_f32_16x16x32_bf16 v[82:85], v[152:155], v[192:195], v[82:85]
	v_mfma_f32_16x16x32_bf16 v[74:77], v[160:163], v[192:195], v[74:77]
	v_mfma_f32_16x16x32_bf16 v[126:129], v[156:159], v[172:175], v[126:129]
	v_mfma_f32_16x16x32_bf16 v[122:125], v[164:167], v[172:175], v[122:125]
	v_mfma_f32_16x16x32_bf16 v[114:117], v[156:159], v[180:183], v[114:117]
	v_mfma_f32_16x16x32_bf16 v[106:109], v[164:167], v[180:183], v[106:109]
	v_mfma_f32_16x16x32_bf16 v[98:101], v[156:159], v[188:191], v[98:101]
	v_mfma_f32_16x16x32_bf16 v[90:93], v[164:167], v[188:191], v[90:93]
	v_mfma_f32_16x16x32_bf16 v[82:85], v[156:159], v[196:199], v[82:85]
	v_mfma_f32_16x16x32_bf16 v[74:77], v[164:167], v[196:199], v[74:77]
	v_mfma_f32_16x16x32_bf16 v[118:121], v[200:203], v[168:171], v[118:121]
	v_mfma_f32_16x16x32_bf16 v[110:113], v[208:211], v[168:171], v[110:113]
	v_mfma_f32_16x16x32_bf16 v[102:105], v[200:203], v[176:179], v[102:105]
	v_mfma_f32_16x16x32_bf16 v[94:97], v[208:211], v[176:179], v[94:97]
	v_mfma_f32_16x16x32_bf16 v[86:89], v[200:203], v[184:187], v[86:89]
	v_mfma_f32_16x16x32_bf16 v[78:81], v[208:211], v[184:187], v[78:81]
	v_mfma_f32_16x16x32_bf16 v[70:73], v[200:203], v[192:195], v[70:73]
	v_mfma_f32_16x16x32_bf16 v[66:69], v[208:211], v[192:195], v[66:69]
	v_mfma_f32_16x16x32_bf16 v[118:121], v[204:207], v[172:175], v[118:121]
	v_mfma_f32_16x16x32_bf16 v[110:113], v[212:215], v[172:175], v[110:113]
	v_mfma_f32_16x16x32_bf16 v[102:105], v[204:207], v[180:183], v[102:105]
	v_mfma_f32_16x16x32_bf16 v[94:97], v[212:215], v[180:183], v[94:97]
	v_mfma_f32_16x16x32_bf16 v[86:89], v[204:207], v[188:191], v[86:89]
	v_mfma_f32_16x16x32_bf16 v[78:81], v[212:215], v[188:191], v[78:81]
	v_mfma_f32_16x16x32_bf16 v[70:73], v[204:207], v[196:199], v[70:73]
	v_mfma_f32_16x16x32_bf16 v[66:69], v[212:215], v[196:199], v[66:69]
	s_barrier
	ds_read_b128 v[168:171], v149 offset:16384
	ds_read_b128 v[172:175], v149 offset:17408
	ds_read_b128 v[176:179], v149 offset:18432
	ds_read_b128 v[180:183], v149 offset:19456
	ds_read_b128 v[184:187], v149 offset:20480
	ds_read_b128 v[188:191], v149 offset:21504
	ds_read_b128 v[192:195], v149 offset:22528
	ds_read_b128 v[196:199], v149 offset:23552
	s_add_i32 s28, s74, s67
	v_lshl_add_u64 v[144:145], s[52:53], 0, v[134:135]
	s_mov_b32 m0, s28
	s_nop 0
	global_load_lds_dwordx4 v[144:145], off
	v_lshl_add_u64 v[216:217], s[52:53], 0, v[130:131]
	s_add_i32 m0, s28, 0x2000
	s_nop 0
	global_load_lds_dwordx4 v[216:217], off
	s_mov_b32 m0, s49
	v_lshl_add_u64 v[218:219], s[54:55], 0, v[136:137]
	global_load_lds_dwordx4 v[218:219], off
	v_lshl_add_u64 v[220:221], s[54:55], 0, v[132:133]
	s_mov_b32 m0, s68
	s_nop 0
	global_load_lds_dwordx4 v[220:221], off
	s_add_u32 s28, s52, 0x100000
	s_addc_u32 s29, s53, 0
	s_add_i32 s82, s75, s67
	v_lshl_add_u64 v[226:227], s[28:29], 0, v[134:135]
	s_mov_b32 m0, s82
	s_nop 0
	global_load_lds_dwordx4 v[226:227], off
	v_lshl_add_u64 v[226:227], s[28:29], 0, v[130:131]
	s_add_i32 m0, s82, 0x2000
	s_nop 0
	global_load_lds_dwordx4 v[226:227], off
	s_waitcnt vmcnt(8)
	s_waitcnt lgkmcnt(0)
	s_barrier
	v_mfma_f32_16x16x32_bf16 v[62:65], v[152:155], v[168:171], v[62:65]
	v_mfma_f32_16x16x32_bf16 v[58:61], v[160:163], v[168:171], v[58:61]
	v_mfma_f32_16x16x32_bf16 v[54:57], v[152:155], v[176:179], v[54:57]
	v_mfma_f32_16x16x32_bf16 v[46:49], v[160:163], v[176:179], v[46:49]
	v_mfma_f32_16x16x32_bf16 v[38:41], v[152:155], v[184:187], v[38:41]
	v_mfma_f32_16x16x32_bf16 v[30:33], v[160:163], v[184:187], v[30:33]
	v_mfma_f32_16x16x32_bf16 v[22:25], v[152:155], v[192:195], v[22:25]
	v_mfma_f32_16x16x32_bf16 v[14:17], v[160:163], v[192:195], v[14:17]
	v_mfma_f32_16x16x32_bf16 v[62:65], v[156:159], v[172:175], v[62:65]
	v_mfma_f32_16x16x32_bf16 v[58:61], v[164:167], v[172:175], v[58:61]
	v_mfma_f32_16x16x32_bf16 v[54:57], v[156:159], v[180:183], v[54:57]
	v_mfma_f32_16x16x32_bf16 v[46:49], v[164:167], v[180:183], v[46:49]
	v_mfma_f32_16x16x32_bf16 v[38:41], v[156:159], v[188:191], v[38:41]
	v_mfma_f32_16x16x32_bf16 v[30:33], v[164:167], v[188:191], v[30:33]
	v_mfma_f32_16x16x32_bf16 v[22:25], v[156:159], v[196:199], v[22:25]
	v_mfma_f32_16x16x32_bf16 v[14:17], v[164:167], v[196:199], v[14:17]
	v_mfma_f32_16x16x32_bf16 v[50:53], v[200:203], v[168:171], v[50:53]
	v_mfma_f32_16x16x32_bf16 v[42:45], v[208:211], v[168:171], v[42:45]
	v_mfma_f32_16x16x32_bf16 v[34:37], v[200:203], v[176:179], v[34:37]
	v_mfma_f32_16x16x32_bf16 v[26:29], v[208:211], v[176:179], v[26:29]
	v_mfma_f32_16x16x32_bf16 v[18:21], v[200:203], v[184:187], v[18:21]
	v_mfma_f32_16x16x32_bf16 v[10:13], v[208:211], v[184:187], v[10:13]
	v_mfma_f32_16x16x32_bf16 v[6:9], v[200:203], v[192:195], v[6:9]
	v_mfma_f32_16x16x32_bf16 v[2:5], v[208:211], v[192:195], v[2:5]
	v_mfma_f32_16x16x32_bf16 v[50:53], v[204:207], v[172:175], v[50:53]
	v_mfma_f32_16x16x32_bf16 v[42:45], v[212:215], v[172:175], v[42:45]
	v_mfma_f32_16x16x32_bf16 v[34:37], v[204:207], v[180:183], v[34:37]
	v_mfma_f32_16x16x32_bf16 v[26:29], v[212:215], v[180:183], v[26:29]
	v_mfma_f32_16x16x32_bf16 v[18:21], v[204:207], v[188:191], v[18:21]
	v_mfma_f32_16x16x32_bf16 v[10:13], v[212:215], v[188:191], v[10:13]
	v_mfma_f32_16x16x32_bf16 v[6:9], v[204:207], v[196:199], v[6:9]
	v_mfma_f32_16x16x32_bf16 v[2:5], v[212:215], v[196:199], v[2:5]
	s_add_i32 s82, 0, 0x18000
	v_add_u32_e32 v151, s82, v146
	s_barrier
	ds_read_b128 v[152:155], v151
	ds_read_b128 v[156:159], v151 offset:1024
	ds_read_b128 v[160:163], v151 offset:2048
	ds_read_b128 v[164:167], v151 offset:3072
	ds_read_b128 v[200:203], v151 offset:16384
	ds_read_b128 v[204:207], v151 offset:17408
	ds_read_b128 v[208:211], v151 offset:18432
	ds_read_b128 v[212:215], v151 offset:19456
	s_add_u32 s28, s54, 0x100000
	s_addc_u32 s29, s55, 0
	s_mov_b32 m0, s69
	v_lshl_add_u64 v[226:227], s[28:29], 0, v[136:137]
	ds_read_b128 v[168:171], v149 offset:32768
	ds_read_b128 v[172:175], v149 offset:33792
	ds_read_b128 v[176:179], v149 offset:34816
	ds_read_b128 v[180:183], v149 offset:35840
	ds_read_b128 v[184:187], v149 offset:36864
	ds_read_b128 v[188:191], v149 offset:37888
	ds_read_b128 v[192:195], v149 offset:38912
	ds_read_b128 v[196:199], v149 offset:39936
	global_load_lds_dwordx4 v[226:227], off
	v_lshl_add_u64 v[226:227], s[28:29], 0, v[132:133]
	s_mov_b32 m0, s70
	s_nop 0
	global_load_lds_dwordx4 v[226:227], off
	s_waitcnt vmcnt(8)
	s_waitcnt lgkmcnt(0)
	s_barrier
	v_mfma_f32_16x16x32_bf16 v[126:129], v[152:155], v[168:171], v[126:129]
	v_mfma_f32_16x16x32_bf16 v[122:125], v[160:163], v[168:171], v[122:125]
	v_mfma_f32_16x16x32_bf16 v[114:117], v[152:155], v[176:179], v[114:117]
	v_mfma_f32_16x16x32_bf16 v[106:109], v[160:163], v[176:179], v[106:109]
	v_mfma_f32_16x16x32_bf16 v[98:101], v[152:155], v[184:187], v[98:101]
	v_mfma_f32_16x16x32_bf16 v[90:93], v[160:163], v[184:187], v[90:93]
	v_mfma_f32_16x16x32_bf16 v[82:85], v[152:155], v[192:195], v[82:85]
	v_mfma_f32_16x16x32_bf16 v[74:77], v[160:163], v[192:195], v[74:77]
	v_mfma_f32_16x16x32_bf16 v[126:129], v[156:159], v[172:175], v[126:129]
	v_mfma_f32_16x16x32_bf16 v[122:125], v[164:167], v[172:175], v[122:125]
	v_mfma_f32_16x16x32_bf16 v[114:117], v[156:159], v[180:183], v[114:117]
	v_mfma_f32_16x16x32_bf16 v[106:109], v[164:167], v[180:183], v[106:109]
	v_mfma_f32_16x16x32_bf16 v[98:101], v[156:159], v[188:191], v[98:101]
	v_mfma_f32_16x16x32_bf16 v[90:93], v[164:167], v[188:191], v[90:93]
	v_mfma_f32_16x16x32_bf16 v[82:85], v[156:159], v[196:199], v[82:85]
	v_mfma_f32_16x16x32_bf16 v[74:77], v[164:167], v[196:199], v[74:77]
	v_mfma_f32_16x16x32_bf16 v[118:121], v[200:203], v[168:171], v[118:121]
	v_mfma_f32_16x16x32_bf16 v[110:113], v[208:211], v[168:171], v[110:113]
	v_mfma_f32_16x16x32_bf16 v[102:105], v[200:203], v[176:179], v[102:105]
	v_mfma_f32_16x16x32_bf16 v[94:97], v[208:211], v[176:179], v[94:97]
	v_mfma_f32_16x16x32_bf16 v[86:89], v[200:203], v[184:187], v[86:89]
	v_mfma_f32_16x16x32_bf16 v[78:81], v[208:211], v[184:187], v[78:81]
	v_mfma_f32_16x16x32_bf16 v[70:73], v[200:203], v[192:195], v[70:73]
	v_mfma_f32_16x16x32_bf16 v[66:69], v[208:211], v[192:195], v[66:69]
	v_mfma_f32_16x16x32_bf16 v[118:121], v[204:207], v[172:175], v[118:121]
	v_mfma_f32_16x16x32_bf16 v[110:113], v[212:215], v[172:175], v[110:113]
	v_mfma_f32_16x16x32_bf16 v[102:105], v[204:207], v[180:183], v[102:105]
	v_mfma_f32_16x16x32_bf16 v[94:97], v[212:215], v[180:183], v[94:97]
	v_mfma_f32_16x16x32_bf16 v[86:89], v[204:207], v[188:191], v[86:89]
	v_mfma_f32_16x16x32_bf16 v[78:81], v[212:215], v[188:191], v[78:81]
	v_mfma_f32_16x16x32_bf16 v[70:73], v[204:207], v[196:199], v[70:73]
	v_mfma_f32_16x16x32_bf16 v[66:69], v[212:215], v[196:199], v[66:69]
	s_barrier
	ds_read_b128 v[168:171], v149 offset:49152
	ds_read_b128 v[172:175], v149 offset:50176
	ds_read_b128 v[176:179], v149 offset:51200
	ds_read_b128 v[180:183], v149 offset:52224
	ds_read_b128 v[184:187], v149 offset:53248
	ds_read_b128 v[188:191], v149 offset:54272
	ds_read_b128 v[192:195], v149 offset:55296
	ds_read_b128 v[196:199], v149 offset:56320
	s_add_i32 s54, 0, 0x1c000
	s_add_i32 s28, s82, s67
	v_lshl_add_u64 v[144:145], v[144:145], 0, s[22:23]
	s_mov_b32 m0, s28
	s_nop 0
	global_load_lds_dwordx4 v[144:145], off
	v_lshl_add_u64 v[144:145], v[216:217], 0, s[22:23]
	s_add_i32 m0, s28, 0x2000
	s_nop 0
	global_load_lds_dwordx4 v[144:145], off
	s_mov_b32 m0, s72
	v_lshl_add_u64 v[144:145], v[218:219], 0, s[22:23]
	global_load_lds_dwordx4 v[144:145], off
	v_lshl_add_u64 v[144:145], v[220:221], 0, s[22:23]
	s_mov_b32 m0, s73
	s_nop 0
	global_load_lds_dwordx4 v[144:145], off
	s_add_u32 s28, s52, 0x100080
	s_addc_u32 s29, s53, 0
	s_add_i32 s52, s54, s67
	v_lshl_add_u64 v[144:145], s[28:29], 0, v[134:135]
	s_mov_b32 m0, s52
	s_nop 0
	global_load_lds_dwordx4 v[144:145], off
	v_lshl_add_u64 v[144:145], s[28:29], 0, v[130:131]
	s_add_i32 m0, s52, 0x2000
	s_nop 0
	global_load_lds_dwordx4 v[144:145], off
	s_waitcnt vmcnt(8)
	s_waitcnt lgkmcnt(0)
	s_barrier
	v_mfma_f32_16x16x32_bf16 v[62:65], v[152:155], v[168:171], v[62:65]
	v_mfma_f32_16x16x32_bf16 v[58:61], v[160:163], v[168:171], v[58:61]
	v_mfma_f32_16x16x32_bf16 v[54:57], v[152:155], v[176:179], v[54:57]
	v_mfma_f32_16x16x32_bf16 v[46:49], v[160:163], v[176:179], v[46:49]
	v_mfma_f32_16x16x32_bf16 v[38:41], v[152:155], v[184:187], v[38:41]
	v_mfma_f32_16x16x32_bf16 v[30:33], v[160:163], v[184:187], v[30:33]
	v_mfma_f32_16x16x32_bf16 v[22:25], v[152:155], v[192:195], v[22:25]
	v_mfma_f32_16x16x32_bf16 v[14:17], v[160:163], v[192:195], v[14:17]
	v_mfma_f32_16x16x32_bf16 v[62:65], v[156:159], v[172:175], v[62:65]
	v_mfma_f32_16x16x32_bf16 v[58:61], v[164:167], v[172:175], v[58:61]
	v_mfma_f32_16x16x32_bf16 v[54:57], v[156:159], v[180:183], v[54:57]
	v_mfma_f32_16x16x32_bf16 v[46:49], v[164:167], v[180:183], v[46:49]
	v_mfma_f32_16x16x32_bf16 v[38:41], v[156:159], v[188:191], v[38:41]
	v_mfma_f32_16x16x32_bf16 v[30:33], v[164:167], v[188:191], v[30:33]
	v_mfma_f32_16x16x32_bf16 v[22:25], v[156:159], v[196:199], v[22:25]
	v_mfma_f32_16x16x32_bf16 v[14:17], v[164:167], v[196:199], v[14:17]
	v_mfma_f32_16x16x32_bf16 v[50:53], v[200:203], v[168:171], v[50:53]
	v_mfma_f32_16x16x32_bf16 v[42:45], v[208:211], v[168:171], v[42:45]
	v_mfma_f32_16x16x32_bf16 v[34:37], v[200:203], v[176:179], v[34:37]
	v_mfma_f32_16x16x32_bf16 v[26:29], v[208:211], v[176:179], v[26:29]
	v_mfma_f32_16x16x32_bf16 v[18:21], v[200:203], v[184:187], v[18:21]
	v_mfma_f32_16x16x32_bf16 v[10:13], v[208:211], v[184:187], v[10:13]
	v_mfma_f32_16x16x32_bf16 v[6:9], v[200:203], v[192:195], v[6:9]
	v_mfma_f32_16x16x32_bf16 v[2:5], v[208:211], v[192:195], v[2:5]
	v_mfma_f32_16x16x32_bf16 v[50:53], v[204:207], v[172:175], v[50:53]
	v_mfma_f32_16x16x32_bf16 v[42:45], v[212:215], v[172:175], v[42:45]
	v_mfma_f32_16x16x32_bf16 v[34:37], v[204:207], v[180:183], v[34:37]
	v_mfma_f32_16x16x32_bf16 v[26:29], v[212:215], v[180:183], v[26:29]
	v_mfma_f32_16x16x32_bf16 v[18:21], v[204:207], v[188:191], v[18:21]
	v_mfma_f32_16x16x32_bf16 v[10:13], v[212:215], v[188:191], v[10:13]
	v_mfma_f32_16x16x32_bf16 v[6:9], v[204:207], v[196:199], v[6:9]
	v_mfma_f32_16x16x32_bf16 v[2:5], v[212:215], v[196:199], v[2:5]
	s_add_i32 s81, s81, 2
	s_add_u32 s39, s39, 0x100
	s_addc_u32 s41, s41, 0
	s_add_u32 s50, s50, 0x100
	s_addc_u32 s51, s51, 0
	s_cmp_gt_u32 s81, 61
	s_barrier
	s_cbranch_scc0 .LBB0_2485
	v_lshl_add_u32 v152, s48, 8, v1
	v_lshl_or_b32 v144, s80, 8, v147
	v_ashrrev_i32_e32 v153, 31, v152
	v_ashrrev_i32_e32 v145, 31, v144
	v_lshlrev_b64 v[154:155], 13, v[152:153]
	v_lshl_add_u64 v[154:155], s[18:19], 0, v[154:155]
	v_lshlrev_b64 v[156:157], 1, v[144:145]
	v_lshl_add_u64 v[144:145], v[154:155], 0, v[156:157]
	v_cvt_pk_bf16_f32 v126, v126, v127
	v_cvt_pk_bf16_f32 v127, v128, v129
	v_cvt_pk_bf16_f32 v128, v122, v123
	v_cvt_pk_bf16_f32 v129, v124, v125
	global_store_dwordx4 v[144:145], v[126:129], off
	v_cvt_pk_bf16_f32 v118, v118, v119
	v_cvt_pk_bf16_f32 v119, v120, v121
	v_cvt_pk_bf16_f32 v120, v110, v111
	v_or_b32_e32 v110, 16, v152
	v_ashrrev_i32_e32 v111, 31, v110
	v_lshlrev_b64 v[110:111], 13, v[110:111]
	v_lshl_add_u64 v[110:111], s[18:19], 0, v[110:111]
	v_cvt_pk_bf16_f32 v121, v112, v113
	global_store_dwordx4 v[144:145], v[118:121], off offset:256
	s_mov_b32 s48, s40
	s_mov_b32 s80, s38
	v_lshl_add_u64 v[118:119], v[110:111], 0, v[156:157]
	v_cvt_pk_bf16_f32 v110, v114, v115
	v_cvt_pk_bf16_f32 v111, v116, v117
	v_cvt_pk_bf16_f32 v112, v106, v107
	v_cvt_pk_bf16_f32 v113, v108, v109
	global_store_dwordx4 v[118:119], v[110:113], off
	v_cvt_pk_bf16_f32 v102, v102, v103
	v_cvt_pk_bf16_f32 v103, v104, v105
	v_cvt_pk_bf16_f32 v104, v94, v95
	v_or_b32_e32 v94, 32, v152
	v_ashrrev_i32_e32 v95, 31, v94
	v_lshlrev_b64 v[94:95], 13, v[94:95]
	v_lshl_add_u64 v[94:95], s[18:19], 0, v[94:95]
	v_cvt_pk_bf16_f32 v105, v96, v97
	global_store_dwordx4 v[118:119], v[102:105], off offset:256
	s_mov_b64 s[52:53], s[46:47]
	s_mov_b64 s[50:51], s[44:45]
	v_lshl_add_u64 v[102:103], v[94:95], 0, v[156:157]
	v_cvt_pk_bf16_f32 v94, v98, v99
	v_cvt_pk_bf16_f32 v95, v100, v101
	v_cvt_pk_bf16_f32 v96, v90, v91
	v_cvt_pk_bf16_f32 v97, v92, v93
	global_store_dwordx4 v[102:103], v[94:97], off
	v_cvt_pk_bf16_f32 v86, v86, v87
	v_cvt_pk_bf16_f32 v87, v88, v89
	v_cvt_pk_bf16_f32 v88, v78, v79
	v_or_b32_e32 v78, 48, v152
	v_ashrrev_i32_e32 v79, 31, v78
	v_lshlrev_b64 v[78:79], 13, v[78:79]
	v_lshl_add_u64 v[78:79], s[18:19], 0, v[78:79]
	v_cvt_pk_bf16_f32 v89, v80, v81
	global_store_dwordx4 v[102:103], v[86:89], off offset:256
	s_nop 1
	v_lshl_add_u64 v[86:87], v[78:79], 0, v[156:157]
	v_cvt_pk_bf16_f32 v78, v82, v83
	v_cvt_pk_bf16_f32 v79, v84, v85
	v_cvt_pk_bf16_f32 v80, v74, v75
	v_cvt_pk_bf16_f32 v81, v76, v77
	global_store_dwordx4 v[86:87], v[78:81], off
	v_cvt_pk_bf16_f32 v70, v70, v71
	v_cvt_pk_bf16_f32 v71, v72, v73
	v_cvt_pk_bf16_f32 v72, v66, v67
	v_cvt_pk_bf16_f32 v73, v68, v69
	global_store_dwordx4 v[86:87], v[70:73], off offset:256
	v_cvt_pk_bf16_f32 v62, v62, v63
	v_cvt_pk_bf16_f32 v63, v64, v65
	v_cvt_pk_bf16_f32 v64, v58, v59
	v_add_co_u32_e32 v58, vcc, s76, v144
	v_lshl_add_u64 v[66:67], v[144:145], 0, s[20:21]
	s_nop 0
	v_addc_co_u32_e32 v59, vcc, 0, v145, vcc
	v_cvt_pk_bf16_f32 v65, v60, v61
	global_store_dwordx4 v[58:59], v[62:65], off
	v_cvt_pk_bf16_f32 v50, v50, v51
	v_cvt_pk_bf16_f32 v51, v52, v53
	v_cvt_pk_bf16_f32 v52, v42, v43
	v_cvt_pk_bf16_f32 v53, v44, v45
	global_store_dwordx4 v[66:67], v[50:53], off offset:256
	v_cvt_pk_bf16_f32 v42, v54, v55
	v_cvt_pk_bf16_f32 v43, v56, v57
	v_cvt_pk_bf16_f32 v44, v46, v47
	v_add_co_u32_e32 v46, vcc, s77, v144
	s_nop 0
	v_lshl_add_u64 v[50:51], v[144:145], 0, s[26:27]
	v_addc_co_u32_e32 v47, vcc, 0, v145, vcc
	v_cvt_pk_bf16_f32 v45, v48, v49
	global_store_dwordx4 v[46:47], v[42:45], off
	v_cvt_pk_bf16_f32 v34, v34, v35
	v_cvt_pk_bf16_f32 v35, v36, v37
	v_cvt_pk_bf16_f32 v36, v26, v27
	v_cvt_pk_bf16_f32 v37, v28, v29
	global_store_dwordx4 v[50:51], v[34:37], off offset:256
	v_cvt_pk_bf16_f32 v26, v38, v39
	v_cvt_pk_bf16_f32 v27, v40, v41
	v_cvt_pk_bf16_f32 v28, v30, v31
	v_add_co_u32_e32 v30, vcc, s78, v144
	s_nop 0
	v_lshl_add_u64 v[34:35], v[144:145], 0, s[34:35]
	v_addc_co_u32_e32 v31, vcc, 0, v145, vcc
	v_cvt_pk_bf16_f32 v29, v32, v33
	global_store_dwordx4 v[30:31], v[26:29], off
	v_cvt_pk_bf16_f32 v18, v18, v19
	v_cvt_pk_bf16_f32 v19, v20, v21
	v_cvt_pk_bf16_f32 v20, v10, v11
	v_cvt_pk_bf16_f32 v21, v12, v13
	global_store_dwordx4 v[34:35], v[18:21], off offset:256
	v_cvt_pk_bf16_f32 v10, v22, v23
	v_cvt_pk_bf16_f32 v11, v24, v25
	v_cvt_pk_bf16_f32 v12, v14, v15
	v_add_co_u32_e32 v14, vcc, s79, v144
	s_nop 0
	v_lshl_add_u64 v[18:19], v[144:145], 0, s[36:37]
	v_addc_co_u32_e32 v15, vcc, 0, v145, vcc
	s_and_b64 vcc, exec, s[6:7]
	v_cvt_pk_bf16_f32 v13, v16, v17
	global_store_dwordx4 v[14:15], v[10:13], off
	v_cvt_pk_bf16_f32 v6, v6, v7
	v_cvt_pk_bf16_f32 v7, v8, v9
	v_cvt_pk_bf16_f32 v8, v2, v3
	v_cvt_pk_bf16_f32 v9, v4, v5
	global_store_dwordx4 v[18:19], v[6:9], off offset:256
	s_cbranch_vccz .LBB0_2478
	s_waitcnt vmcnt(0)
	s_cmpk_gt_u32 s66, 0xff
	s_cbranch_scc1 .LBB0_2489
	s_barrier

.LBB0_3048:
	ds_read_b128 v[154:157], v150
	ds_read_b128 v[158:161], v150 offset:1024
	ds_read_b128 v[162:165], v150 offset:2048
	ds_read_b128 v[166:169], v150 offset:3072
	ds_read_b128 v[202:205], v152
	ds_read_b128 v[206:209], v152 offset:1024
	ds_read_b128 v[210:213], v152 offset:2048
	ds_read_b128 v[214:217], v152 offset:3072
	s_add_u32 s28, s38, 0xfff00080
	s_addc_u32 s29, s39, -1
	s_cmp_eq_u32 s72, 60
	s_cselect_b32 s45, s37, s29
	s_cselect_b32 s44, s36, s28
	s_cselect_b32 s41, s35, s71
	s_cselect_b32 s40, s34, s21
	v_lshl_add_u64 v[146:147], s[38:39], 0, v[142:143]
	s_add_i32 m0, s23, 0xc000
	ds_read_b128 v[170:173], v151
	ds_read_b128 v[174:177], v151 offset:1024
	ds_read_b128 v[178:181], v151 offset:2048
	ds_read_b128 v[182:185], v151 offset:3072
	ds_read_b128 v[186:189], v151 offset:4096
	ds_read_b128 v[190:193], v151 offset:5120
	ds_read_b128 v[194:197], v151 offset:6144
	ds_read_b128 v[198:201], v151 offset:7168
	global_load_lds_dwordx4 v[146:147], off
	v_lshl_add_u64 v[146:147], s[38:39], 0, v[140:141]
	s_add_i32 m0, s23, 0xe000
	s_nop 0
	global_load_lds_dwordx4 v[146:147], off
	s_waitcnt vmcnt(8)
	s_waitcnt lgkmcnt(0)
	s_barrier
	v_mfma_f32_16x16x32_bf16 v[126:129], v[154:157], v[170:173], v[126:129]
	v_mfma_f32_16x16x32_bf16 v[122:125], v[162:165], v[170:173], v[122:125]
	v_mfma_f32_16x16x32_bf16 v[118:121], v[154:157], v[178:181], v[118:121]
	v_mfma_f32_16x16x32_bf16 v[110:113], v[162:165], v[178:181], v[110:113]
	v_mfma_f32_16x16x32_bf16 v[102:105], v[154:157], v[186:189], v[102:105]
	v_mfma_f32_16x16x32_bf16 v[94:97], v[162:165], v[186:189], v[94:97]
	v_mfma_f32_16x16x32_bf16 v[86:89], v[154:157], v[194:197], v[86:89]
	v_mfma_f32_16x16x32_bf16 v[78:81], v[162:165], v[194:197], v[78:81]
	v_mfma_f32_16x16x32_bf16 v[126:129], v[158:161], v[174:177], v[126:129]
	v_mfma_f32_16x16x32_bf16 v[122:125], v[166:169], v[174:177], v[122:125]
	v_mfma_f32_16x16x32_bf16 v[118:121], v[158:161], v[182:185], v[118:121]
	v_mfma_f32_16x16x32_bf16 v[110:113], v[166:169], v[182:185], v[110:113]
	v_mfma_f32_16x16x32_bf16 v[102:105], v[158:161], v[190:193], v[102:105]
	v_mfma_f32_16x16x32_bf16 v[94:97], v[166:169], v[190:193], v[94:97]
	v_mfma_f32_16x16x32_bf16 v[86:89], v[158:161], v[198:201], v[86:89]
	v_mfma_f32_16x16x32_bf16 v[78:81], v[166:169], v[198:201], v[78:81]
	v_mfma_f32_16x16x32_bf16 v[114:117], v[202:205], v[170:173], v[114:117]
	v_mfma_f32_16x16x32_bf16 v[106:109], v[210:213], v[170:173], v[106:109]
	v_mfma_f32_16x16x32_bf16 v[98:101], v[202:205], v[178:181], v[98:101]
	v_mfma_f32_16x16x32_bf16 v[90:93], v[210:213], v[178:181], v[90:93]
	v_mfma_f32_16x16x32_bf16 v[82:85], v[202:205], v[186:189], v[82:85]
	v_mfma_f32_16x16x32_bf16 v[74:77], v[210:213], v[186:189], v[74:77]
	v_mfma_f32_16x16x32_bf16 v[70:73], v[202:205], v[194:197], v[70:73]
	v_mfma_f32_16x16x32_bf16 v[66:69], v[210:213], v[194:197], v[66:69]
	v_mfma_f32_16x16x32_bf16 v[114:117], v[206:209], v[174:177], v[114:117]
	v_mfma_f32_16x16x32_bf16 v[106:109], v[214:217], v[174:177], v[106:109]
	v_mfma_f32_16x16x32_bf16 v[98:101], v[206:209], v[182:185], v[98:101]
	v_mfma_f32_16x16x32_bf16 v[90:93], v[214:217], v[182:185], v[90:93]
	v_mfma_f32_16x16x32_bf16 v[82:85], v[206:209], v[190:193], v[82:85]
	v_mfma_f32_16x16x32_bf16 v[74:77], v[214:217], v[190:193], v[74:77]
	v_mfma_f32_16x16x32_bf16 v[70:73], v[206:209], v[198:201], v[70:73]
	v_mfma_f32_16x16x32_bf16 v[66:69], v[214:217], v[198:201], v[66:69]
	s_barrier
	ds_read_b128 v[170:173], v151 offset:16384
	ds_read_b128 v[174:177], v151 offset:17408
	ds_read_b128 v[178:181], v151 offset:18432
	ds_read_b128 v[182:185], v151 offset:19456
	ds_read_b128 v[186:189], v151 offset:20480
	ds_read_b128 v[190:193], v151 offset:21504
	ds_read_b128 v[194:197], v151 offset:22528
	ds_read_b128 v[198:201], v151 offset:23552
	s_add_i32 s28, s64, s54
	v_lshl_add_u64 v[146:147], s[40:41], 0, v[134:135]
	s_mov_b32 m0, s28
	s_nop 0
	global_load_lds_dwordx4 v[146:147], off
	v_lshl_add_u64 v[218:219], s[40:41], 0, v[130:131]
	s_add_i32 m0, s28, 0x2000
	s_nop 0
	global_load_lds_dwordx4 v[218:219], off
	s_mov_b32 m0, s23
	v_lshl_add_u64 v[220:221], s[44:45], 0, v[136:137]
	global_load_lds_dwordx4 v[220:221], off
	v_lshl_add_u64 v[222:223], s[44:45], 0, v[132:133]
	s_mov_b32 m0, s27
	s_nop 0
	global_load_lds_dwordx4 v[222:223], off
	s_add_u32 s28, s40, 0x100000
	s_addc_u32 s29, s41, 0
	s_add_i32 s73, s65, s54
	v_lshl_add_u64 v[226:227], s[28:29], 0, v[134:135]
	s_mov_b32 m0, s73
	s_nop 0
	global_load_lds_dwordx4 v[226:227], off
	v_lshl_add_u64 v[226:227], s[28:29], 0, v[130:131]
	s_add_i32 m0, s73, 0x2000
	s_nop 0
	global_load_lds_dwordx4 v[226:227], off
	s_waitcnt vmcnt(8)
	s_waitcnt lgkmcnt(0)
	s_barrier
	v_mfma_f32_16x16x32_bf16 v[62:65], v[154:157], v[170:173], v[62:65]
	v_mfma_f32_16x16x32_bf16 v[58:61], v[162:165], v[170:173], v[58:61]
	v_mfma_f32_16x16x32_bf16 v[54:57], v[154:157], v[178:181], v[54:57]
	v_mfma_f32_16x16x32_bf16 v[46:49], v[162:165], v[178:181], v[46:49]
	v_mfma_f32_16x16x32_bf16 v[38:41], v[154:157], v[186:189], v[38:41]
	v_mfma_f32_16x16x32_bf16 v[30:33], v[162:165], v[186:189], v[30:33]
	v_mfma_f32_16x16x32_bf16 v[22:25], v[154:157], v[194:197], v[22:25]
	v_mfma_f32_16x16x32_bf16 v[14:17], v[162:165], v[194:197], v[14:17]
	v_mfma_f32_16x16x32_bf16 v[62:65], v[158:161], v[174:177], v[62:65]
	v_mfma_f32_16x16x32_bf16 v[58:61], v[166:169], v[174:177], v[58:61]
	v_mfma_f32_16x16x32_bf16 v[54:57], v[158:161], v[182:185], v[54:57]
	v_mfma_f32_16x16x32_bf16 v[46:49], v[166:169], v[182:185], v[46:49]
	v_mfma_f32_16x16x32_bf16 v[38:41], v[158:161], v[190:193], v[38:41]
	v_mfma_f32_16x16x32_bf16 v[30:33], v[166:169], v[190:193], v[30:33]
	v_mfma_f32_16x16x32_bf16 v[22:25], v[158:161], v[198:201], v[22:25]
	v_mfma_f32_16x16x32_bf16 v[14:17], v[166:169], v[198:201], v[14:17]
	v_mfma_f32_16x16x32_bf16 v[50:53], v[202:205], v[170:173], v[50:53]
	v_mfma_f32_16x16x32_bf16 v[42:45], v[210:213], v[170:173], v[42:45]
	v_mfma_f32_16x16x32_bf16 v[34:37], v[202:205], v[178:181], v[34:37]
	v_mfma_f32_16x16x32_bf16 v[26:29], v[210:213], v[178:181], v[26:29]
	v_mfma_f32_16x16x32_bf16 v[18:21], v[202:205], v[186:189], v[18:21]
	v_mfma_f32_16x16x32_bf16 v[10:13], v[210:213], v[186:189], v[10:13]
	v_mfma_f32_16x16x32_bf16 v[6:9], v[202:205], v[194:197], v[6:9]
	v_mfma_f32_16x16x32_bf16 v[2:5], v[210:213], v[194:197], v[2:5]
	v_mfma_f32_16x16x32_bf16 v[50:53], v[206:209], v[174:177], v[50:53]
	v_mfma_f32_16x16x32_bf16 v[42:45], v[214:217], v[174:177], v[42:45]
	v_mfma_f32_16x16x32_bf16 v[34:37], v[206:209], v[182:185], v[34:37]
	v_mfma_f32_16x16x32_bf16 v[26:29], v[214:217], v[182:185], v[26:29]
	v_mfma_f32_16x16x32_bf16 v[18:21], v[206:209], v[190:193], v[18:21]
	v_mfma_f32_16x16x32_bf16 v[10:13], v[214:217], v[190:193], v[10:13]
	v_mfma_f32_16x16x32_bf16 v[6:9], v[206:209], v[198:201], v[6:9]
	v_mfma_f32_16x16x32_bf16 v[2:5], v[214:217], v[198:201], v[2:5]
	s_add_i32 s73, 0, 0x18000
	v_add_u32_e32 v153, s73, v148
	s_barrier
	ds_read_b128 v[154:157], v153
	ds_read_b128 v[158:161], v153 offset:1024
	ds_read_b128 v[162:165], v153 offset:2048
	ds_read_b128 v[166:169], v153 offset:3072
	ds_read_b128 v[202:205], v153 offset:16384
	ds_read_b128 v[206:209], v153 offset:17408
	ds_read_b128 v[210:213], v153 offset:18432
	ds_read_b128 v[214:217], v153 offset:19456
	s_add_u32 s28, s44, 0x100000
	s_addc_u32 s29, s45, 0
	s_mov_b32 m0, s55
	v_lshl_add_u64 v[226:227], s[28:29], 0, v[136:137]
	ds_read_b128 v[170:173], v151 offset:32768
	ds_read_b128 v[174:177], v151 offset:33792
	ds_read_b128 v[178:181], v151 offset:34816
	ds_read_b128 v[182:185], v151 offset:35840
	ds_read_b128 v[186:189], v151 offset:36864
	ds_read_b128 v[190:193], v151 offset:37888
	ds_read_b128 v[194:197], v151 offset:38912
	ds_read_b128 v[198:201], v151 offset:39936
	global_load_lds_dwordx4 v[226:227], off
	v_lshl_add_u64 v[226:227], s[28:29], 0, v[132:133]
	s_mov_b32 m0, s56
	s_nop 0
	global_load_lds_dwordx4 v[226:227], off
	s_waitcnt vmcnt(8)
	s_waitcnt lgkmcnt(0)
	s_barrier
	v_mfma_f32_16x16x32_bf16 v[126:129], v[154:157], v[170:173], v[126:129]
	v_mfma_f32_16x16x32_bf16 v[122:125], v[162:165], v[170:173], v[122:125]
	v_mfma_f32_16x16x32_bf16 v[118:121], v[154:157], v[178:181], v[118:121]
	v_mfma_f32_16x16x32_bf16 v[110:113], v[162:165], v[178:181], v[110:113]
	v_mfma_f32_16x16x32_bf16 v[102:105], v[154:157], v[186:189], v[102:105]
	v_mfma_f32_16x16x32_bf16 v[94:97], v[162:165], v[186:189], v[94:97]
	v_mfma_f32_16x16x32_bf16 v[86:89], v[154:157], v[194:197], v[86:89]
	v_mfma_f32_16x16x32_bf16 v[78:81], v[162:165], v[194:197], v[78:81]
	v_mfma_f32_16x16x32_bf16 v[126:129], v[158:161], v[174:177], v[126:129]
	v_mfma_f32_16x16x32_bf16 v[122:125], v[166:169], v[174:177], v[122:125]
	v_mfma_f32_16x16x32_bf16 v[118:121], v[158:161], v[182:185], v[118:121]
	v_mfma_f32_16x16x32_bf16 v[110:113], v[166:169], v[182:185], v[110:113]
	v_mfma_f32_16x16x32_bf16 v[102:105], v[158:161], v[190:193], v[102:105]
	v_mfma_f32_16x16x32_bf16 v[94:97], v[166:169], v[190:193], v[94:97]
	v_mfma_f32_16x16x32_bf16 v[86:89], v[158:161], v[198:201], v[86:89]
	v_mfma_f32_16x16x32_bf16 v[78:81], v[166:169], v[198:201], v[78:81]
	v_mfma_f32_16x16x32_bf16 v[114:117], v[202:205], v[170:173], v[114:117]
	v_mfma_f32_16x16x32_bf16 v[106:109], v[210:213], v[170:173], v[106:109]
	v_mfma_f32_16x16x32_bf16 v[98:101], v[202:205], v[178:181], v[98:101]
	v_mfma_f32_16x16x32_bf16 v[90:93], v[210:213], v[178:181], v[90:93]
	v_mfma_f32_16x16x32_bf16 v[82:85], v[202:205], v[186:189], v[82:85]
	v_mfma_f32_16x16x32_bf16 v[74:77], v[210:213], v[186:189], v[74:77]
	v_mfma_f32_16x16x32_bf16 v[70:73], v[202:205], v[194:197], v[70:73]
	v_mfma_f32_16x16x32_bf16 v[66:69], v[210:213], v[194:197], v[66:69]
	v_mfma_f32_16x16x32_bf16 v[114:117], v[206:209], v[174:177], v[114:117]
	v_mfma_f32_16x16x32_bf16 v[106:109], v[214:217], v[174:177], v[106:109]
	v_mfma_f32_16x16x32_bf16 v[98:101], v[206:209], v[182:185], v[98:101]
	v_mfma_f32_16x16x32_bf16 v[90:93], v[214:217], v[182:185], v[90:93]
	v_mfma_f32_16x16x32_bf16 v[82:85], v[206:209], v[190:193], v[82:85]
	v_mfma_f32_16x16x32_bf16 v[74:77], v[214:217], v[190:193], v[74:77]
	v_mfma_f32_16x16x32_bf16 v[70:73], v[206:209], v[198:201], v[70:73]
	v_mfma_f32_16x16x32_bf16 v[66:69], v[214:217], v[198:201], v[66:69]
	s_barrier
	ds_read_b128 v[170:173], v151 offset:49152
	ds_read_b128 v[174:177], v151 offset:50176
	ds_read_b128 v[178:181], v151 offset:51200
	ds_read_b128 v[182:185], v151 offset:52224
	ds_read_b128 v[186:189], v151 offset:53248
	ds_read_b128 v[190:193], v151 offset:54272
	ds_read_b128 v[194:197], v151 offset:55296
	ds_read_b128 v[198:201], v151 offset:56320
	s_add_i32 s44, 0, 0x1c000
	s_add_i32 s28, s73, s54
	v_lshl_add_u64 v[146:147], v[146:147], 0, s[6:7]
	s_mov_b32 m0, s28
	s_nop 0
	global_load_lds_dwordx4 v[146:147], off
	v_lshl_add_u64 v[146:147], v[218:219], 0, s[6:7]
	s_add_i32 m0, s28, 0x2000
	s_nop 0
	global_load_lds_dwordx4 v[146:147], off
	s_mov_b32 m0, s59
	v_lshl_add_u64 v[146:147], v[220:221], 0, s[6:7]
	global_load_lds_dwordx4 v[146:147], off
	v_lshl_add_u64 v[146:147], v[222:223], 0, s[6:7]
	s_mov_b32 m0, s60
	s_nop 0
	global_load_lds_dwordx4 v[146:147], off
	s_add_u32 s28, s40, 0x100080
	s_addc_u32 s29, s41, 0
	s_add_i32 s40, s44, s54
	v_lshl_add_u64 v[146:147], s[28:29], 0, v[134:135]
	s_mov_b32 m0, s40
	s_nop 0
	global_load_lds_dwordx4 v[146:147], off
	v_lshl_add_u64 v[146:147], s[28:29], 0, v[130:131]
	s_add_i32 m0, s40, 0x2000
	s_nop 0
	global_load_lds_dwordx4 v[146:147], off
	s_waitcnt vmcnt(8)
	s_waitcnt lgkmcnt(0)
	s_barrier
	v_mfma_f32_16x16x32_bf16 v[62:65], v[154:157], v[170:173], v[62:65]
	v_mfma_f32_16x16x32_bf16 v[58:61], v[162:165], v[170:173], v[58:61]
	v_mfma_f32_16x16x32_bf16 v[54:57], v[154:157], v[178:181], v[54:57]
	v_mfma_f32_16x16x32_bf16 v[46:49], v[162:165], v[178:181], v[46:49]
	v_mfma_f32_16x16x32_bf16 v[38:41], v[154:157], v[186:189], v[38:41]
	v_mfma_f32_16x16x32_bf16 v[30:33], v[162:165], v[186:189], v[30:33]
	v_mfma_f32_16x16x32_bf16 v[22:25], v[154:157], v[194:197], v[22:25]
	v_mfma_f32_16x16x32_bf16 v[14:17], v[162:165], v[194:197], v[14:17]
	v_mfma_f32_16x16x32_bf16 v[62:65], v[158:161], v[174:177], v[62:65]
	v_mfma_f32_16x16x32_bf16 v[58:61], v[166:169], v[174:177], v[58:61]
	v_mfma_f32_16x16x32_bf16 v[54:57], v[158:161], v[182:185], v[54:57]
	v_mfma_f32_16x16x32_bf16 v[46:49], v[166:169], v[182:185], v[46:49]
	v_mfma_f32_16x16x32_bf16 v[38:41], v[158:161], v[190:193], v[38:41]
	v_mfma_f32_16x16x32_bf16 v[30:33], v[166:169], v[190:193], v[30:33]
	v_mfma_f32_16x16x32_bf16 v[22:25], v[158:161], v[198:201], v[22:25]
	v_mfma_f32_16x16x32_bf16 v[14:17], v[166:169], v[198:201], v[14:17]
	v_mfma_f32_16x16x32_bf16 v[50:53], v[202:205], v[170:173], v[50:53]
	v_mfma_f32_16x16x32_bf16 v[42:45], v[210:213], v[170:173], v[42:45]
	v_mfma_f32_16x16x32_bf16 v[34:37], v[202:205], v[178:181], v[34:37]
	v_mfma_f32_16x16x32_bf16 v[26:29], v[210:213], v[178:181], v[26:29]
	v_mfma_f32_16x16x32_bf16 v[18:21], v[202:205], v[186:189], v[18:21]
	v_mfma_f32_16x16x32_bf16 v[10:13], v[210:213], v[186:189], v[10:13]
	v_mfma_f32_16x16x32_bf16 v[6:9], v[202:205], v[194:197], v[6:9]
	v_mfma_f32_16x16x32_bf16 v[2:5], v[210:213], v[194:197], v[2:5]
	v_mfma_f32_16x16x32_bf16 v[50:53], v[206:209], v[174:177], v[50:53]
	v_mfma_f32_16x16x32_bf16 v[42:45], v[214:217], v[174:177], v[42:45]
	v_mfma_f32_16x16x32_bf16 v[34:37], v[206:209], v[182:185], v[34:37]
	v_mfma_f32_16x16x32_bf16 v[26:29], v[214:217], v[182:185], v[26:29]
	v_mfma_f32_16x16x32_bf16 v[18:21], v[206:209], v[190:193], v[18:21]
	v_mfma_f32_16x16x32_bf16 v[10:13], v[214:217], v[190:193], v[10:13]
	v_mfma_f32_16x16x32_bf16 v[6:9], v[206:209], v[198:201], v[6:9]
	v_mfma_f32_16x16x32_bf16 v[2:5], v[214:217], v[198:201], v[2:5]
	s_add_i32 s72, s72, 2
	s_add_u32 s21, s21, 0x100
	s_addc_u32 s71, s71, 0
	s_add_u32 s38, s38, 0x100
	s_addc_u32 s39, s39, 0
	s_cmp_gt_u32 s72, 61
	s_barrier
	s_cbranch_scc0 .LBB0_3048
	s_cmp_lt_i32 s70, 2
	s_cbranch_scc1 .LBB0_3053
	s_cmp_eq_u32 s70, 2
	s_mov_b64 s[38:39], -1
	s_cbranch_scc0 .LBB0_3052
	v_lshl_add_u32 v146, s26, 8, v1
	v_or_b32_e32 v156, 16, v146
	v_ashrrev_i32_e32 v147, 31, v146
	v_ashrrev_i32_e32 v157, 31, v156
	v_lshlrev_b64 v[154:155], 10, v[146:147]
	v_lshlrev_b64 v[156:157], 10, v[156:157]
	v_lshl_add_u64 v[154:155], v[138:139], 0, v[154:155]
	v_lshl_add_u64 v[156:157], v[138:139], 0, v[156:157]
	global_store_dwordx4 v[154:155], v[126:129], off
	global_store_dwordx4 v[154:155], v[122:125], off offset:16
	global_store_dwordx4 v[154:155], v[114:117], off offset:512
	global_store_dwordx4 v[154:155], v[106:109], off offset:528
	global_store_dwordx4 v[156:157], v[118:121], off
	global_store_dwordx4 v[156:157], v[110:113], off offset:16
	global_store_dwordx4 v[156:157], v[98:101], off offset:512
	global_store_dwordx4 v[156:157], v[90:93], off offset:528
	v_or_b32_e32 v156, 32, v146
	v_ashrrev_i32_e32 v157, 31, v156
	v_lshlrev_b64 v[156:157], 10, v[156:157]
	v_or_b32_e32 v146, 48, v146
	v_lshl_add_u64 v[156:157], v[138:139], 0, v[156:157]
	v_ashrrev_i32_e32 v147, 31, v146
	global_store_dwordx4 v[156:157], v[102:105], off
	global_store_dwordx4 v[156:157], v[94:97], off offset:16
	global_store_dwordx4 v[156:157], v[82:85], off offset:512
	global_store_dwordx4 v[156:157], v[74:77], off offset:528
	v_lshlrev_b64 v[146:147], 10, v[146:147]
	v_add_co_u32_e32 v156, vcc, s66, v154
	v_lshl_add_u64 v[146:147], v[138:139], 0, v[146:147]
	s_nop 0
	v_addc_co_u32_e32 v157, vcc, 0, v155, vcc
	global_store_dwordx4 v[146:147], v[86:89], off
	global_store_dwordx4 v[146:147], v[78:81], off offset:16
	global_store_dwordx4 v[146:147], v[70:73], off offset:512
	global_store_dwordx4 v[146:147], v[66:69], off offset:528
	v_lshl_add_u64 v[146:147], v[154:155], 0, s[8:9]
	global_store_dwordx4 v[156:157], v[62:65], off
	global_store_dwordx4 v[146:147], v[58:61], off offset:16
	global_store_dwordx4 v[146:147], v[50:53], off offset:512
	global_store_dwordx4 v[146:147], v[42:45], off offset:528
	v_add_co_u32_e32 v156, vcc, s67, v154
	v_lshl_add_u64 v[146:147], v[154:155], 0, s[12:13]
	s_nop 0
	v_addc_co_u32_e32 v157, vcc, 0, v155, vcc
	global_store_dwordx4 v[156:157], v[54:57], off
	global_store_dwordx4 v[146:147], v[46:49], off offset:16
	global_store_dwordx4 v[146:147], v[34:37], off offset:512
	global_store_dwordx4 v[146:147], v[26:29], off offset:528
	v_add_co_u32_e32 v156, vcc, s68, v154
	v_lshl_add_u64 v[146:147], v[154:155], 0, s[14:15]
	s_nop 0
	v_addc_co_u32_e32 v157, vcc, 0, v155, vcc
	global_store_dwordx4 v[156:157], v[38:41], off
	global_store_dwordx4 v[146:147], v[30:33], off offset:16
	global_store_dwordx4 v[146:147], v[18:21], off offset:512
	global_store_dwordx4 v[146:147], v[10:13], off offset:528
	v_lshl_add_u64 v[146:147], v[154:155], 0, s[16:17]
	v_add_co_u32_e32 v154, vcc, 0x2c000, v154
	s_mov_b64 s[38:39], 0
	s_nop 0
	v_addc_co_u32_e32 v155, vcc, 0, v155, vcc
	global_store_dwordx4 v[154:155], v[22:25], off
	global_store_dwordx4 v[146:147], v[14:17], off offset:16
	global_store_dwordx4 v[146:147], v[6:9], off offset:512
	global_store_dwordx4 v[146:147], v[2:5], off offset:528

.LBB0_4133:
	ds_read_b128 v[152:155], v148
	ds_read_b128 v[156:159], v148 offset:1024
	ds_read_b128 v[160:163], v148 offset:2048
	ds_read_b128 v[164:167], v148 offset:3072
	ds_read_b128 v[200:203], v150
	ds_read_b128 v[204:207], v150 offset:1024
	ds_read_b128 v[208:211], v150 offset:2048
	ds_read_b128 v[212:215], v150 offset:3072
	s_add_u32 s28, s38, 0xfff00080
	s_addc_u32 s29, s39, -1
	s_cmp_eq_u32 s60, 60
	s_cselect_b32 s45, s27, s29
	s_cselect_b32 s44, s26, s28
	s_cselect_b32 s41, s35, s23
	s_cselect_b32 s40, s34, s21
	v_lshl_add_u64 v[144:145], s[38:39], 0, v[140:141]
	s_add_i32 m0, s37, 0xc000
	ds_read_b128 v[168:171], v149
	ds_read_b128 v[172:175], v149 offset:1024
	ds_read_b128 v[176:179], v149 offset:2048
	ds_read_b128 v[180:183], v149 offset:3072
	ds_read_b128 v[184:187], v149 offset:4096
	ds_read_b128 v[188:191], v149 offset:5120
	ds_read_b128 v[192:195], v149 offset:6144
	ds_read_b128 v[196:199], v149 offset:7168
	global_load_lds_dwordx4 v[144:145], off
	v_lshl_add_u64 v[144:145], s[38:39], 0, v[138:139]
	s_add_i32 m0, s37, 0xe000
	s_nop 0
	global_load_lds_dwordx4 v[144:145], off
	s_waitcnt vmcnt(8)
	s_waitcnt lgkmcnt(0)
	s_barrier
	v_mfma_f32_16x16x32_bf16 v[126:129], v[152:155], v[168:171], v[126:129]
	v_mfma_f32_16x16x32_bf16 v[122:125], v[160:163], v[168:171], v[122:125]
	v_mfma_f32_16x16x32_bf16 v[114:117], v[152:155], v[176:179], v[114:117]
	v_mfma_f32_16x16x32_bf16 v[106:109], v[160:163], v[176:179], v[106:109]
	v_mfma_f32_16x16x32_bf16 v[98:101], v[152:155], v[184:187], v[98:101]
	v_mfma_f32_16x16x32_bf16 v[90:93], v[160:163], v[184:187], v[90:93]
	v_mfma_f32_16x16x32_bf16 v[82:85], v[152:155], v[192:195], v[82:85]
	v_mfma_f32_16x16x32_bf16 v[74:77], v[160:163], v[192:195], v[74:77]
	v_mfma_f32_16x16x32_bf16 v[126:129], v[156:159], v[172:175], v[126:129]
	v_mfma_f32_16x16x32_bf16 v[122:125], v[164:167], v[172:175], v[122:125]
	v_mfma_f32_16x16x32_bf16 v[114:117], v[156:159], v[180:183], v[114:117]
	v_mfma_f32_16x16x32_bf16 v[106:109], v[164:167], v[180:183], v[106:109]
	v_mfma_f32_16x16x32_bf16 v[98:101], v[156:159], v[188:191], v[98:101]
	v_mfma_f32_16x16x32_bf16 v[90:93], v[164:167], v[188:191], v[90:93]
	v_mfma_f32_16x16x32_bf16 v[82:85], v[156:159], v[196:199], v[82:85]
	v_mfma_f32_16x16x32_bf16 v[74:77], v[164:167], v[196:199], v[74:77]
	v_mfma_f32_16x16x32_bf16 v[118:121], v[200:203], v[168:171], v[118:121]
	v_mfma_f32_16x16x32_bf16 v[110:113], v[208:211], v[168:171], v[110:113]
	v_mfma_f32_16x16x32_bf16 v[102:105], v[200:203], v[176:179], v[102:105]
	v_mfma_f32_16x16x32_bf16 v[94:97], v[208:211], v[176:179], v[94:97]
	v_mfma_f32_16x16x32_bf16 v[86:89], v[200:203], v[184:187], v[86:89]
	v_mfma_f32_16x16x32_bf16 v[78:81], v[208:211], v[184:187], v[78:81]
	v_mfma_f32_16x16x32_bf16 v[70:73], v[200:203], v[192:195], v[70:73]
	v_mfma_f32_16x16x32_bf16 v[66:69], v[208:211], v[192:195], v[66:69]
	v_mfma_f32_16x16x32_bf16 v[118:121], v[204:207], v[172:175], v[118:121]
	v_mfma_f32_16x16x32_bf16 v[110:113], v[212:215], v[172:175], v[110:113]
	v_mfma_f32_16x16x32_bf16 v[102:105], v[204:207], v[180:183], v[102:105]
	v_mfma_f32_16x16x32_bf16 v[94:97], v[212:215], v[180:183], v[94:97]
	v_mfma_f32_16x16x32_bf16 v[86:89], v[204:207], v[188:191], v[86:89]
	v_mfma_f32_16x16x32_bf16 v[78:81], v[212:215], v[188:191], v[78:81]
	v_mfma_f32_16x16x32_bf16 v[70:73], v[204:207], v[196:199], v[70:73]
	v_mfma_f32_16x16x32_bf16 v[66:69], v[212:215], v[196:199], v[66:69]
	s_barrier
	ds_read_b128 v[168:171], v149 offset:16384
	ds_read_b128 v[172:175], v149 offset:17408
	ds_read_b128 v[176:179], v149 offset:18432
	ds_read_b128 v[180:183], v149 offset:19456
	ds_read_b128 v[184:187], v149 offset:20480
	ds_read_b128 v[188:191], v149 offset:21504
	ds_read_b128 v[192:195], v149 offset:22528
	ds_read_b128 v[196:199], v149 offset:23552
	s_add_i32 s28, s53, s31
	v_lshl_add_u64 v[144:145], s[40:41], 0, v[134:135]
	s_mov_b32 m0, s28
	s_nop 0
	global_load_lds_dwordx4 v[144:145], off
	v_lshl_add_u64 v[216:217], s[40:41], 0, v[130:131]
	s_add_i32 m0, s28, 0x2000
	s_nop 0
	global_load_lds_dwordx4 v[216:217], off
	s_mov_b32 m0, s37
	v_lshl_add_u64 v[218:219], s[44:45], 0, v[136:137]
	global_load_lds_dwordx4 v[218:219], off
	v_lshl_add_u64 v[220:221], s[44:45], 0, v[132:133]
	s_mov_b32 m0, s46
	s_nop 0
	global_load_lds_dwordx4 v[220:221], off
	s_add_u32 s28, s40, 0x100000
	s_addc_u32 s29, s41, 0
	s_add_i32 s61, s54, s31
	v_lshl_add_u64 v[226:227], s[28:29], 0, v[134:135]
	s_mov_b32 m0, s61
	s_nop 0
	global_load_lds_dwordx4 v[226:227], off
	v_lshl_add_u64 v[226:227], s[28:29], 0, v[130:131]
	s_add_i32 m0, s61, 0x2000
	s_nop 0
	global_load_lds_dwordx4 v[226:227], off
	s_waitcnt vmcnt(8)
	s_waitcnt lgkmcnt(0)
	s_barrier
	v_mfma_f32_16x16x32_bf16 v[62:65], v[152:155], v[168:171], v[62:65]
	v_mfma_f32_16x16x32_bf16 v[58:61], v[160:163], v[168:171], v[58:61]
	v_mfma_f32_16x16x32_bf16 v[54:57], v[152:155], v[176:179], v[54:57]
	v_mfma_f32_16x16x32_bf16 v[46:49], v[160:163], v[176:179], v[46:49]
	v_mfma_f32_16x16x32_bf16 v[38:41], v[152:155], v[184:187], v[38:41]
	v_mfma_f32_16x16x32_bf16 v[30:33], v[160:163], v[184:187], v[30:33]
	v_mfma_f32_16x16x32_bf16 v[22:25], v[152:155], v[192:195], v[22:25]
	v_mfma_f32_16x16x32_bf16 v[14:17], v[160:163], v[192:195], v[14:17]
	v_mfma_f32_16x16x32_bf16 v[62:65], v[156:159], v[172:175], v[62:65]
	v_mfma_f32_16x16x32_bf16 v[58:61], v[164:167], v[172:175], v[58:61]
	v_mfma_f32_16x16x32_bf16 v[54:57], v[156:159], v[180:183], v[54:57]
	v_mfma_f32_16x16x32_bf16 v[46:49], v[164:167], v[180:183], v[46:49]
	v_mfma_f32_16x16x32_bf16 v[38:41], v[156:159], v[188:191], v[38:41]
	v_mfma_f32_16x16x32_bf16 v[30:33], v[164:167], v[188:191], v[30:33]
	v_mfma_f32_16x16x32_bf16 v[22:25], v[156:159], v[196:199], v[22:25]
	v_mfma_f32_16x16x32_bf16 v[14:17], v[164:167], v[196:199], v[14:17]
	v_mfma_f32_16x16x32_bf16 v[50:53], v[200:203], v[168:171], v[50:53]
	v_mfma_f32_16x16x32_bf16 v[42:45], v[208:211], v[168:171], v[42:45]
	v_mfma_f32_16x16x32_bf16 v[34:37], v[200:203], v[176:179], v[34:37]
	v_mfma_f32_16x16x32_bf16 v[26:29], v[208:211], v[176:179], v[26:29]
	v_mfma_f32_16x16x32_bf16 v[18:21], v[200:203], v[184:187], v[18:21]
	v_mfma_f32_16x16x32_bf16 v[10:13], v[208:211], v[184:187], v[10:13]
	v_mfma_f32_16x16x32_bf16 v[6:9], v[200:203], v[192:195], v[6:9]
	v_mfma_f32_16x16x32_bf16 v[2:5], v[208:211], v[192:195], v[2:5]
	v_mfma_f32_16x16x32_bf16 v[50:53], v[204:207], v[172:175], v[50:53]
	v_mfma_f32_16x16x32_bf16 v[42:45], v[212:215], v[172:175], v[42:45]
	v_mfma_f32_16x16x32_bf16 v[34:37], v[204:207], v[180:183], v[34:37]
	v_mfma_f32_16x16x32_bf16 v[26:29], v[212:215], v[180:183], v[26:29]
	v_mfma_f32_16x16x32_bf16 v[18:21], v[204:207], v[188:191], v[18:21]
	v_mfma_f32_16x16x32_bf16 v[10:13], v[212:215], v[188:191], v[10:13]
	v_mfma_f32_16x16x32_bf16 v[6:9], v[204:207], v[196:199], v[6:9]
	v_mfma_f32_16x16x32_bf16 v[2:5], v[212:215], v[196:199], v[2:5]
	s_add_i32 s61, 0, 0x18000
	v_add_u32_e32 v151, s61, v146
	s_barrier
	ds_read_b128 v[152:155], v151
	ds_read_b128 v[156:159], v151 offset:1024
	ds_read_b128 v[160:163], v151 offset:2048
	ds_read_b128 v[164:167], v151 offset:3072
	ds_read_b128 v[200:203], v151 offset:16384
	ds_read_b128 v[204:207], v151 offset:17408
	ds_read_b128 v[208:211], v151 offset:18432
	ds_read_b128 v[212:215], v151 offset:19456
	s_add_u32 s28, s44, 0x100000
	s_addc_u32 s29, s45, 0
	s_mov_b32 m0, s47
	v_lshl_add_u64 v[226:227], s[28:29], 0, v[136:137]
	ds_read_b128 v[168:171], v149 offset:32768
	ds_read_b128 v[172:175], v149 offset:33792
	ds_read_b128 v[176:179], v149 offset:34816
	ds_read_b128 v[180:183], v149 offset:35840
	ds_read_b128 v[184:187], v149 offset:36864
	ds_read_b128 v[188:191], v149 offset:37888
	ds_read_b128 v[192:195], v149 offset:38912
	ds_read_b128 v[196:199], v149 offset:39936
	global_load_lds_dwordx4 v[226:227], off
	v_lshl_add_u64 v[226:227], s[28:29], 0, v[132:133]
	s_mov_b32 m0, s48
	s_nop 0
	global_load_lds_dwordx4 v[226:227], off
	s_waitcnt vmcnt(8)
	s_waitcnt lgkmcnt(0)
	s_barrier
	v_mfma_f32_16x16x32_bf16 v[126:129], v[152:155], v[168:171], v[126:129]
	v_mfma_f32_16x16x32_bf16 v[122:125], v[160:163], v[168:171], v[122:125]
	v_mfma_f32_16x16x32_bf16 v[114:117], v[152:155], v[176:179], v[114:117]
	v_mfma_f32_16x16x32_bf16 v[106:109], v[160:163], v[176:179], v[106:109]
	v_mfma_f32_16x16x32_bf16 v[98:101], v[152:155], v[184:187], v[98:101]
	v_mfma_f32_16x16x32_bf16 v[90:93], v[160:163], v[184:187], v[90:93]
	v_mfma_f32_16x16x32_bf16 v[82:85], v[152:155], v[192:195], v[82:85]
	v_mfma_f32_16x16x32_bf16 v[74:77], v[160:163], v[192:195], v[74:77]
	v_mfma_f32_16x16x32_bf16 v[126:129], v[156:159], v[172:175], v[126:129]
	v_mfma_f32_16x16x32_bf16 v[122:125], v[164:167], v[172:175], v[122:125]
	v_mfma_f32_16x16x32_bf16 v[114:117], v[156:159], v[180:183], v[114:117]
	v_mfma_f32_16x16x32_bf16 v[106:109], v[164:167], v[180:183], v[106:109]
	v_mfma_f32_16x16x32_bf16 v[98:101], v[156:159], v[188:191], v[98:101]
	v_mfma_f32_16x16x32_bf16 v[90:93], v[164:167], v[188:191], v[90:93]
	v_mfma_f32_16x16x32_bf16 v[82:85], v[156:159], v[196:199], v[82:85]
	v_mfma_f32_16x16x32_bf16 v[74:77], v[164:167], v[196:199], v[74:77]
	v_mfma_f32_16x16x32_bf16 v[118:121], v[200:203], v[168:171], v[118:121]
	v_mfma_f32_16x16x32_bf16 v[110:113], v[208:211], v[168:171], v[110:113]
	v_mfma_f32_16x16x32_bf16 v[102:105], v[200:203], v[176:179], v[102:105]
	v_mfma_f32_16x16x32_bf16 v[94:97], v[208:211], v[176:179], v[94:97]
	v_mfma_f32_16x16x32_bf16 v[86:89], v[200:203], v[184:187], v[86:89]
	v_mfma_f32_16x16x32_bf16 v[78:81], v[208:211], v[184:187], v[78:81]
	v_mfma_f32_16x16x32_bf16 v[70:73], v[200:203], v[192:195], v[70:73]
	v_mfma_f32_16x16x32_bf16 v[66:69], v[208:211], v[192:195], v[66:69]
	v_mfma_f32_16x16x32_bf16 v[118:121], v[204:207], v[172:175], v[118:121]
	v_mfma_f32_16x16x32_bf16 v[110:113], v[212:215], v[172:175], v[110:113]
	v_mfma_f32_16x16x32_bf16 v[102:105], v[204:207], v[180:183], v[102:105]
	v_mfma_f32_16x16x32_bf16 v[94:97], v[212:215], v[180:183], v[94:97]
	v_mfma_f32_16x16x32_bf16 v[86:89], v[204:207], v[188:191], v[86:89]
	v_mfma_f32_16x16x32_bf16 v[78:81], v[212:215], v[188:191], v[78:81]
	v_mfma_f32_16x16x32_bf16 v[70:73], v[204:207], v[196:199], v[70:73]
	v_mfma_f32_16x16x32_bf16 v[66:69], v[212:215], v[196:199], v[66:69]
	s_barrier
	ds_read_b128 v[168:171], v149 offset:49152
	ds_read_b128 v[172:175], v149 offset:50176
	ds_read_b128 v[176:179], v149 offset:51200
	ds_read_b128 v[180:183], v149 offset:52224
	ds_read_b128 v[184:187], v149 offset:53248
	ds_read_b128 v[188:191], v149 offset:54272
	ds_read_b128 v[192:195], v149 offset:55296
	ds_read_b128 v[196:199], v149 offset:56320
	s_add_i32 s44, 0, 0x1c000
	s_add_i32 s28, s61, s31
	v_lshl_add_u64 v[144:145], v[144:145], 0, s[12:13]
	s_mov_b32 m0, s28
	s_nop 0
	global_load_lds_dwordx4 v[144:145], off
	v_lshl_add_u64 v[144:145], v[216:217], 0, s[12:13]
	s_add_i32 m0, s28, 0x2000
	s_nop 0
	global_load_lds_dwordx4 v[144:145], off
	s_mov_b32 m0, s50
	v_lshl_add_u64 v[144:145], v[218:219], 0, s[12:13]
	global_load_lds_dwordx4 v[144:145], off
	v_lshl_add_u64 v[144:145], v[220:221], 0, s[12:13]
	s_mov_b32 m0, s51
	s_nop 0
	global_load_lds_dwordx4 v[144:145], off
	s_add_u32 s28, s40, 0x100080
	s_addc_u32 s29, s41, 0
	s_add_i32 s40, s44, s31
	v_lshl_add_u64 v[144:145], s[28:29], 0, v[134:135]
	s_mov_b32 m0, s40
	s_nop 0
	global_load_lds_dwordx4 v[144:145], off
	v_lshl_add_u64 v[144:145], s[28:29], 0, v[130:131]
	s_add_i32 m0, s40, 0x2000
	s_nop 0
	global_load_lds_dwordx4 v[144:145], off
	s_waitcnt vmcnt(8)
	s_waitcnt lgkmcnt(0)
	s_barrier
	v_mfma_f32_16x16x32_bf16 v[62:65], v[152:155], v[168:171], v[62:65]
	v_mfma_f32_16x16x32_bf16 v[58:61], v[160:163], v[168:171], v[58:61]
	v_mfma_f32_16x16x32_bf16 v[54:57], v[152:155], v[176:179], v[54:57]
	v_mfma_f32_16x16x32_bf16 v[46:49], v[160:163], v[176:179], v[46:49]
	v_mfma_f32_16x16x32_bf16 v[38:41], v[152:155], v[184:187], v[38:41]
	v_mfma_f32_16x16x32_bf16 v[30:33], v[160:163], v[184:187], v[30:33]
	v_mfma_f32_16x16x32_bf16 v[22:25], v[152:155], v[192:195], v[22:25]
	v_mfma_f32_16x16x32_bf16 v[14:17], v[160:163], v[192:195], v[14:17]
	v_mfma_f32_16x16x32_bf16 v[62:65], v[156:159], v[172:175], v[62:65]
	v_mfma_f32_16x16x32_bf16 v[58:61], v[164:167], v[172:175], v[58:61]
	v_mfma_f32_16x16x32_bf16 v[54:57], v[156:159], v[180:183], v[54:57]
	v_mfma_f32_16x16x32_bf16 v[46:49], v[164:167], v[180:183], v[46:49]
	v_mfma_f32_16x16x32_bf16 v[38:41], v[156:159], v[188:191], v[38:41]
	v_mfma_f32_16x16x32_bf16 v[30:33], v[164:167], v[188:191], v[30:33]
	v_mfma_f32_16x16x32_bf16 v[22:25], v[156:159], v[196:199], v[22:25]
	v_mfma_f32_16x16x32_bf16 v[14:17], v[164:167], v[196:199], v[14:17]
	v_mfma_f32_16x16x32_bf16 v[50:53], v[200:203], v[168:171], v[50:53]
	v_mfma_f32_16x16x32_bf16 v[42:45], v[208:211], v[168:171], v[42:45]
	v_mfma_f32_16x16x32_bf16 v[34:37], v[200:203], v[176:179], v[34:37]
	v_mfma_f32_16x16x32_bf16 v[26:29], v[208:211], v[176:179], v[26:29]
	v_mfma_f32_16x16x32_bf16 v[18:21], v[200:203], v[184:187], v[18:21]
	v_mfma_f32_16x16x32_bf16 v[10:13], v[208:211], v[184:187], v[10:13]
	v_mfma_f32_16x16x32_bf16 v[6:9], v[200:203], v[192:195], v[6:9]
	v_mfma_f32_16x16x32_bf16 v[2:5], v[208:211], v[192:195], v[2:5]
	v_mfma_f32_16x16x32_bf16 v[50:53], v[204:207], v[172:175], v[50:53]
	v_mfma_f32_16x16x32_bf16 v[42:45], v[212:215], v[172:175], v[42:45]
	v_mfma_f32_16x16x32_bf16 v[34:37], v[204:207], v[180:183], v[34:37]
	v_mfma_f32_16x16x32_bf16 v[26:29], v[212:215], v[180:183], v[26:29]
	v_mfma_f32_16x16x32_bf16 v[18:21], v[204:207], v[188:191], v[18:21]
	v_mfma_f32_16x16x32_bf16 v[10:13], v[212:215], v[188:191], v[10:13]
	v_mfma_f32_16x16x32_bf16 v[6:9], v[204:207], v[196:199], v[6:9]
	v_mfma_f32_16x16x32_bf16 v[2:5], v[212:215], v[196:199], v[2:5]
	s_add_i32 s60, s60, 2
	s_add_u32 s21, s21, 0x100
	s_addc_u32 s23, s23, 0
	s_add_u32 s38, s38, 0x100
	s_addc_u32 s39, s39, 0
	s_cmp_gt_u32 s60, 61
	s_barrier
	s_cbranch_scc0 .LBB0_4133
	v_lshl_add_u32 v152, s36, 8, v1
	v_lshl_or_b32 v144, s59, 8, v147
	v_ashrrev_i32_e32 v153, 31, v152
	v_ashrrev_i32_e32 v145, 31, v144
	v_lshlrev_b64 v[154:155], 13, v[152:153]
	v_lshl_add_u64 v[154:155], s[8:9], 0, v[154:155]
	v_lshlrev_b64 v[156:157], 1, v[144:145]
	v_lshl_add_u64 v[144:145], v[154:155], 0, v[156:157]
	v_cvt_pk_bf16_f32 v126, v126, v127
	v_cvt_pk_bf16_f32 v127, v128, v129
	v_cvt_pk_bf16_f32 v128, v122, v123
	v_cvt_pk_bf16_f32 v129, v124, v125
	global_store_dwordx4 v[144:145], v[126:129], off
	v_cvt_pk_bf16_f32 v118, v118, v119
	v_cvt_pk_bf16_f32 v119, v120, v121
	v_cvt_pk_bf16_f32 v120, v110, v111
	v_or_b32_e32 v110, 16, v152
	v_ashrrev_i32_e32 v111, 31, v110
	v_lshlrev_b64 v[110:111], 13, v[110:111]
	v_lshl_add_u64 v[110:111], s[8:9], 0, v[110:111]
	v_cvt_pk_bf16_f32 v121, v112, v113
	global_store_dwordx4 v[144:145], v[118:121], off offset:256
	s_mov_b32 s36, s22
	s_mov_b32 s59, s20
	v_lshl_add_u64 v[118:119], v[110:111], 0, v[156:157]
	v_cvt_pk_bf16_f32 v110, v114, v115
	v_cvt_pk_bf16_f32 v111, v116, v117
	v_cvt_pk_bf16_f32 v112, v106, v107
	v_cvt_pk_bf16_f32 v113, v108, v109
	global_store_dwordx4 v[118:119], v[110:113], off
	v_cvt_pk_bf16_f32 v102, v102, v103
	v_cvt_pk_bf16_f32 v103, v104, v105
	v_cvt_pk_bf16_f32 v104, v94, v95
	v_or_b32_e32 v94, 32, v152
	v_ashrrev_i32_e32 v95, 31, v94
	v_lshlrev_b64 v[94:95], 13, v[94:95]
	v_lshl_add_u64 v[94:95], s[8:9], 0, v[94:95]
	v_cvt_pk_bf16_f32 v105, v96, v97
	global_store_dwordx4 v[118:119], v[102:105], off offset:256
	s_mov_b64 s[40:41], s[34:35]
	s_mov_b64 s[38:39], s[26:27]
	v_lshl_add_u64 v[102:103], v[94:95], 0, v[156:157]
	v_cvt_pk_bf16_f32 v94, v98, v99
	v_cvt_pk_bf16_f32 v95, v100, v101
	v_cvt_pk_bf16_f32 v96, v90, v91
	v_cvt_pk_bf16_f32 v97, v92, v93
	global_store_dwordx4 v[102:103], v[94:97], off
	v_cvt_pk_bf16_f32 v86, v86, v87
	v_cvt_pk_bf16_f32 v87, v88, v89
	v_cvt_pk_bf16_f32 v88, v78, v79
	v_or_b32_e32 v78, 48, v152
	v_ashrrev_i32_e32 v79, 31, v78
	v_lshlrev_b64 v[78:79], 13, v[78:79]
	v_lshl_add_u64 v[78:79], s[8:9], 0, v[78:79]
	v_cvt_pk_bf16_f32 v89, v80, v81
	global_store_dwordx4 v[102:103], v[86:89], off offset:256
	s_nop 1
	v_lshl_add_u64 v[86:87], v[78:79], 0, v[156:157]
	v_cvt_pk_bf16_f32 v78, v82, v83
	v_cvt_pk_bf16_f32 v79, v84, v85
	v_cvt_pk_bf16_f32 v80, v74, v75
	v_cvt_pk_bf16_f32 v81, v76, v77
	global_store_dwordx4 v[86:87], v[78:81], off
	v_cvt_pk_bf16_f32 v70, v70, v71
	v_cvt_pk_bf16_f32 v71, v72, v73
	v_cvt_pk_bf16_f32 v72, v66, v67
	v_cvt_pk_bf16_f32 v73, v68, v69
	global_store_dwordx4 v[86:87], v[70:73], off offset:256
	v_cvt_pk_bf16_f32 v62, v62, v63
	v_cvt_pk_bf16_f32 v63, v64, v65
	v_cvt_pk_bf16_f32 v64, v58, v59
	v_add_co_u32_e32 v58, vcc, s55, v144
	v_lshl_add_u64 v[66:67], v[144:145], 0, s[6:7]
	s_nop 0
	v_addc_co_u32_e32 v59, vcc, 0, v145, vcc
	v_cvt_pk_bf16_f32 v65, v60, v61
	global_store_dwordx4 v[58:59], v[62:65], off
	v_cvt_pk_bf16_f32 v50, v50, v51
	v_cvt_pk_bf16_f32 v51, v52, v53
	v_cvt_pk_bf16_f32 v52, v42, v43
	v_cvt_pk_bf16_f32 v53, v44, v45
	global_store_dwordx4 v[66:67], v[50:53], off offset:256
	v_cvt_pk_bf16_f32 v42, v54, v55
	v_cvt_pk_bf16_f32 v43, v56, v57
	v_cvt_pk_bf16_f32 v44, v46, v47
	v_add_co_u32_e32 v46, vcc, s56, v144
	s_nop 0
	v_lshl_add_u64 v[50:51], v[144:145], 0, s[14:15]
	v_addc_co_u32_e32 v47, vcc, 0, v145, vcc
	v_cvt_pk_bf16_f32 v45, v48, v49
	global_store_dwordx4 v[46:47], v[42:45], off
	v_cvt_pk_bf16_f32 v34, v34, v35
	v_cvt_pk_bf16_f32 v35, v36, v37
	v_cvt_pk_bf16_f32 v36, v26, v27
	v_cvt_pk_bf16_f32 v37, v28, v29
	global_store_dwordx4 v[50:51], v[34:37], off offset:256
	v_cvt_pk_bf16_f32 v26, v38, v39
	v_cvt_pk_bf16_f32 v27, v40, v41
	v_cvt_pk_bf16_f32 v28, v30, v31
	v_add_co_u32_e32 v30, vcc, s57, v144
	s_nop 0
	v_lshl_add_u64 v[34:35], v[144:145], 0, s[16:17]
	v_addc_co_u32_e32 v31, vcc, 0, v145, vcc
	v_cvt_pk_bf16_f32 v29, v32, v33
	global_store_dwordx4 v[30:31], v[26:29], off
	v_cvt_pk_bf16_f32 v18, v18, v19
	v_cvt_pk_bf16_f32 v19, v20, v21
	v_cvt_pk_bf16_f32 v20, v10, v11
	v_cvt_pk_bf16_f32 v21, v12, v13
	global_store_dwordx4 v[34:35], v[18:21], off offset:256
	v_cvt_pk_bf16_f32 v10, v22, v23
	v_cvt_pk_bf16_f32 v11, v24, v25
	v_cvt_pk_bf16_f32 v12, v14, v15
	v_add_co_u32_e32 v14, vcc, s58, v144
	s_nop 0
	v_lshl_add_u64 v[18:19], v[144:145], 0, s[18:19]
	v_addc_co_u32_e32 v15, vcc, 0, v145, vcc
	s_and_b64 vcc, exec, s[4:5]
	v_cvt_pk_bf16_f32 v13, v16, v17
	global_store_dwordx4 v[14:15], v[10:13], off
	v_cvt_pk_bf16_f32 v6, v6, v7
	v_cvt_pk_bf16_f32 v7, v8, v9
	v_cvt_pk_bf16_f32 v8, v2, v3
	v_cvt_pk_bf16_f32 v9, v4, v5
	global_store_dwordx4 v[18:19], v[6:9], off offset:256
	s_cbranch_vccz .LBB0_4126
	s_waitcnt vmcnt(0)
	s_cmpk_gt_u32 s11, 0xff
	s_cbranch_scc1 .LBB0_4137
	s_barrier
